# attn A/B steady loops: K/V LDS-DMA addresses via SGPR base + 32-bit lane offsets (removes per-tile 64-bit VALU address adds)
# speedup vs baseline: 1.0043x; 1.0043x over previous
; template<int THRL,bool WIN,int DM,int ODM,int DV,int QMODE> __device__ __forceinline__ void attn_unit(const bf16*Qp,const bf16*__restrict__ Kp,const bf16*__restrict__ Vp,bf16*Op,const int q0,const int t_lo,const int NT,const float sink2,char*shm,const float*qgain,const float*qtab,const int b0,const ...
;     ...
;     float v[4][8];
;     #pragma unroll
;     for(int d0=0;d0<4;++d0){
;       #pragma unroll
;       for(int e=0;e<8;++e)v[d0][e]=__builtin_bit_cast(float,((unsigned)(unsigned short)qr[d0][e])<<16);}
;     const int bp=(lane^32)<<2;
;     if constexpr(QMODE==1){
;       float ss=0.f;
;       #pragma unroll
;       for(int d0=0;d0<4;++d0){
;         #pragma unroll
;         for(int e=0;e<8;++e)ss+=v[d0][e]*v[d0][e];}
;       ss+=__builtin_bit_cast(float,__builtin_amdgcn_ds_bpermute(bp,__builtin_bit_cast(int,ss)));
;       const float rn=__builtin_amdgcn_rsqf(ss*(1.f/64.f)+1e-6f);
;       const int trow=qpos>>6,tcol=qpos&63;
;       #pragma unroll
;       for(int d0=0;d0<4;++d0){ const f32x4_t g0=*(const f32x4_t*)(qgain+16*d0+8*hi),g1=*(const f32x4_t*)(qgain+16*d0+8*hi+4);
;         const float g[8]={g0.x,g0.y,g0.z,g0.w,g1.x,g1.y,g1.z,g1.w};
;         #pragma unroll
;         for(int e=0;e<8;++e)v[d0][e]=(v[d0][e]*rn)*g[e];}
.LBB0_382:
	v_lshlrev_b32_e32 v1, 2, v18
	v_or_b32_e32 v18, s13, v205
	v_add_u32_e32 v22, s80, v18
	v_lshlrev_b32_e32 v193, 4, v206
	v_lshlrev_b32_e32 v18, 5, v22
	s_movk_i32 s4, 0x7e0
	v_and_or_b32 v18, v18, s4, v193
	v_ashrrev_i32_e32 v22, 1, v22
	s_movk_i32 s4, 0xffe0
	v_and_or_b32 v22, v22, s4, v193
	v_ashrrev_i32_e32 v23, 31, v22
	v_lshlrev_b32_e32 v18, 2, v18
	v_lshl_add_u64 v[100:101], v[22:23], 2, s[10:11]
	global_load_dwordx4 v[76:79], v1, s[72:73] offset:208
	global_load_dwordx4 v[26:29], v1, s[72:73] offset:144
	global_load_dwordx4 v[30:33], v1, s[72:73] offset:128
	global_load_dwordx4 v[80:83], v1, s[72:73] offset:192
	global_load_dwordx4 v[34:37], v18, s[10:11] offset:48
	global_load_dwordx4 v[38:41], v18, s[10:11] offset:32
	global_load_dwordx4 v[42:45], v18, s[10:11] offset:16
	s_nop 0
	global_load_dwordx4 v[18:21], v18, s[10:11]
	s_nop 0
	global_load_dwordx4 v[58:61], v1, s[72:73] offset:16
	global_load_dwordx4 v[84:87], v1, s[72:73] offset:80
	global_load_dwordx4 v[22:25], v[100:101], off offset:48
	global_load_dwordx4 v[54:57], v[100:101], off offset:32
	global_load_dwordx4 v[88:91], v1, s[72:73]
	global_load_dwordx4 v[92:95], v1, s[72:73] offset:64
	v_lshlrev_b32_e32 v96, 2, v203
	v_xor_b32_e32 v1, 0x80, v96
	global_load_dwordx4 v[96:99], v[100:101], off
	s_nop 0
	global_load_dwordx4 v[100:103], v[100:101], off offset:16
	s_waitcnt vmcnt(19)
	v_and_b32_e32 v153, 0xffff0000, v47
	v_lshlrev_b32_e32 v154, 16, v47
	v_and_b32_e32 v161, 0xffff0000, v46
	s_waitcnt vmcnt(18)
	v_lshlrev_b32_e32 v160, 16, v50
	v_and_b32_e32 v47, 0xffff0000, v50
	v_lshlrev_b32_e32 v46, 16, v46
	v_lshlrev_b32_e32 v152, 16, v51
	v_and_b32_e32 v155, 0xffff0000, v51
	v_pk_mul_f32 v[50:51], v[46:47], v[46:47]
	v_pk_mul_f32 v[162:163], v[160:161], v[160:161]
	v_pk_mul_f32 v[156:157], v[154:155], v[154:155]
	v_add_f32_e32 v50, v50, v163
	v_and_b32_e32 v133, 0xffff0000, v49
	v_lshlrev_b32_e32 v134, 16, v49
	v_and_b32_e32 v145, 0xffff0000, v48
	v_and_b32_e32 v49, 0xffff0000, v52
	v_lshlrev_b32_e32 v48, 16, v48
	v_pk_mul_f32 v[158:159], v[152:153], v[152:153]
	v_add_f32_e32 v50, v156, v50
	v_lshlrev_b32_e32 v132, 16, v53
	v_and_b32_e32 v135, 0xffff0000, v53
	v_lshlrev_b32_e32 v144, 16, v52
	v_pk_mul_f32 v[52:53], v[48:49], v[48:49]
	v_add_f32_e32 v50, v159, v50
	v_pk_mul_f32 v[146:147], v[144:145], v[144:145]
	v_add_f32_e32 v50, v52, v50
	v_pk_mul_f32 v[136:137], v[134:135], v[134:135]
	v_add_f32_e32 v50, v147, v50
	v_pk_mul_f32 v[138:139], v[132:133], v[132:133]
	v_add_f32_e32 v50, v136, v50
	v_add_f32_e32 v50, v139, v50
	v_add_f32_e32 v50, v162, v50
	v_add_f32_e32 v50, v51, v50
	v_add_f32_e32 v50, v158, v50
	v_add_f32_e32 v50, v157, v50
	v_add_f32_e32 v50, v146, v50
	v_add_f32_e32 v50, v53, v50
	v_add_f32_e32 v50, v138, v50
	s_waitcnt vmcnt(17)
	v_lshlrev_b32_e32 v114, 16, v62
	v_add_f32_e32 v50, v137, v50
	v_and_b32_e32 v113, 0xffff0000, v62
	v_fmac_f32_e32 v50, v114, v114
	v_lshlrev_b32_e32 v110, 16, v63
	v_fmac_f32_e32 v50, v113, v113
	v_and_b32_e32 v109, 0xffff0000, v63
	v_fmac_f32_e32 v50, v110, v110
	v_lshlrev_b32_e32 v106, 16, v64
	v_fmac_f32_e32 v50, v109, v109
	v_and_b32_e32 v105, 0xffff0000, v64
	v_fmac_f32_e32 v50, v106, v106
	v_lshlrev_b32_e32 v72, 16, v65
	s_waitcnt vmcnt(16)
	v_lshlrev_b32_e32 v112, 16, v66
	v_and_b32_e32 v115, 0xffff0000, v66
	v_fmac_f32_e32 v50, v105, v105
	v_lshlrev_b32_e32 v70, 16, v69
	v_and_b32_e32 v71, 0xffff0000, v65
	v_and_b32_e32 v73, 0xffff0000, v69
	v_lshlrev_b32_e32 v104, 16, v68
	v_and_b32_e32 v107, 0xffff0000, v68
	v_pk_mov_b32 v[68:69], v[114:115], v[112:113] op_sel:[1,0]
	v_fmac_f32_e32 v50, v72, v72
	v_lshlrev_b32_e32 v108, 16, v67
	v_and_b32_e32 v111, 0xffff0000, v67
	v_pk_mul_f32 v[122:123], v[68:69], v[68:69]
	v_fmac_f32_e32 v50, v71, v71
	v_pk_mov_b32 v[66:67], v[110:111], v[108:109] op_sel:[1,0]
	v_add_f32_e32 v50, v123, v50
	v_pk_mul_f32 v[120:121], v[66:67], v[66:67]
	v_add_f32_e32 v50, v122, v50
	v_pk_mov_b32 v[64:65], v[106:107], v[104:105] op_sel:[1,0]
	v_add_f32_e32 v50, v121, v50
	v_pk_mul_f32 v[118:119], v[64:65], v[64:65]
	v_add_f32_e32 v50, v120, v50
	v_pk_mov_b32 v[62:63], v[72:73], v[70:71] op_sel:[1,0]
	v_add_f32_e32 v50, v119, v50
	v_pk_mul_f32 v[116:117], v[62:63], v[62:63]
	v_add_f32_e32 v50, v118, v50
	v_add_f32_e32 v50, v117, v50
	v_add_f32_e32 v53, v116, v50
	ds_bpermute_b32 v1, v1, v53
	s_waitcnt vmcnt(2)
	v_mov_b32_e32 v50, v94
	v_mov_b32_e32 v141, v61
	v_mov_b32_e32 v61, v87
	v_mov_b32_e32 v120, v92
	s_waitcnt lgkmcnt(0)
	v_add_f32_e32 v1, v53, v1
	v_fmamk_f32 v1, v1, 0x3c800000, v241
	v_rsq_f32_e32 v94, v1
	v_mov_b32_e32 v121, v89
	v_mov_b32_e32 v89, v93
	v_mov_b32_e32 v124, v78
	v_pk_mul_f32 v[92:93], v[94:95], v[134:135] op_sel_hi:[0,1]
	v_mov_b32_e32 v125, v29
	v_mov_b32_e32 v29, v79
	v_mov_b32_e32 v78, v76
	v_mov_b32_e32 v79, v27
	v_mov_b32_e32 v27, v77
	v_mov_b32_e32 v76, v82
	v_mov_b32_e32 v77, v33
	v_mov_b32_e32 v33, v83
	v_mov_b32_e32 v82, v80
	v_mov_b32_e32 v83, v31
	v_pk_mul_f32 v[60:61], v[60:61], v[92:93]
	v_pk_mul_f32 v[92:93], v[94:95], v[112:113] op_sel_hi:[0,1]
	v_mov_b32_e32 v31, v81
	v_pk_mul_f32 v[82:83], v[92:93], v[82:83]
	v_pk_mul_f32 v[92:93], v[94:95], v[114:115] op_sel_hi:[0,1]
	v_pk_mul_f32 v[92:93], v[92:93], v[30:31]
	v_pk_mul_f32 v[30:31], v[94:95], v[108:109] op_sel_hi:[0,1]
	v_pk_mul_f32 v[76:77], v[30:31], v[76:77]
	v_pk_mul_f32 v[30:31], v[94:95], v[110:111] op_sel_hi:[0,1]
	v_pk_mul_f32 v[108:109], v[30:31], v[32:33]
	v_pk_mul_f32 v[30:31], v[94:95], v[104:105] op_sel_hi:[0,1]
	v_pk_mul_f32 v[78:79], v[30:31], v[78:79]
	v_pk_mul_f32 v[30:31], v[94:95], v[106:107] op_sel_hi:[0,1]
	v_pk_mul_f32 v[104:105], v[30:31], v[26:27]
	v_pk_mul_f32 v[26:27], v[94:95], v[70:71] op_sel_hi:[0,1]
	v_pk_mul_f32 v[118:119], v[94:95], v[160:161] op_sel_hi:[0,1]
	v_pk_mul_f32 v[46:47], v[94:95], v[46:47] op_sel_hi:[0,1]
	v_pk_mul_f32 v[70:71], v[26:27], v[124:125]
	v_pk_mul_f32 v[26:27], v[94:95], v[72:73] op_sel_hi:[0,1]
	v_mov_b32_e32 v51, v91
	v_pk_mul_f32 v[118:119], v[120:121], v[118:119]
	v_pk_mul_f32 v[46:47], v[88:89], v[46:47]
	v_pk_mul_f32 v[88:89], v[94:95], v[152:153] op_sel_hi:[0,1]
	v_pk_mul_f32 v[72:73], v[26:27], v[28:29]
	s_waitcnt vmcnt(1)
; __device__ __forceinline__ unsigned cvtpk_s(float lo,float hi){f32x2_t v={lo,hi};bf16x2_t b=__builtin_convertvector(v,bf16x2_t);return __builtin_bit_cast(unsigned,b);}
; #define WAIT_BAR(N) asm volatile("s_waitcnt vmcnt(" #N ") lgkmcnt(0)\n\ts_barrier":::"memory")
;   #define CMASK(P0,P1,t) do{ if constexpr(WIN){ wmask(P0,P1,(t_lo+(t))*KVBLK+4*hi,qpos); } }while(0)
; template<int THRL,bool WIN,int DM,int ODM,int DV,int QMODE> __device__ __forceinline__ void attn_unit(const bf16*Qp,const bf16*__restrict__ Kp,const bf16*__restrict__ Vp,bf16*Op,const int q0,const int t_lo,const int NT,const float sink2,char*shm,const float*qgain,const float*qtab,const int b0,const ...
;     ...
;       for(int h2=0;h2<2;++h2){ const float*tb=qtab+((h2==0?trow:tcol)*16+8*hi)*2;
;         const f32x4_t c0=*(const f32x4_t*)(tb),c1=*(const f32x4_t*)(tb+4),c2=*(const f32x4_t*)(tb+8),c3=*(const f32x4_t*)(tb+12);
;         const float cc[8]={c0.x,c0.z,c1.x,c1.z,c2.x,c2.z,c3.x,c3.z},sn[8]={c0.y,c0.w,c1.y,c1.w,c2.y,c2.w,c3.y,c3.w};
;         #pragma unroll
;         for(int e=0;e<8;++e){ const float x1=v[2*h2][e],x2=v[2*h2+1][e]; v[2*h2][e]=x1*cc[e]-x2*sn[e]; v[2*h2+1][e]=x2*cc[e]+x1*sn[e]; } }
;     } else {
;       const float*tb=qtab+(size_t)qpos*16;
;       const f32x4_t c0=*(const f32x4_t*)(tb),c1=*(const f32x4_t*)(tb+4),c2=*(const f32x4_t*)(tb+8),c3=*(const f32x4_t*)(tb+12);
;       const float cc[8]={c0.x,c0.z,c1.x,c1.z,c2.x,c2.z,c3.x,c3.z},sn[8]={c0.y,c0.w,c1.y,c1.w,c2.y,c2.w,c3.y,c3.w};
;       const float sg=hi?1.f:-1.f;
;       #pragma unroll
;       for(int e=0;e<8;++e){ const float p=__builtin_bit_cast(float,__builtin_amdgcn_ds_bpermute(bp,__builtin_bit_cast(int,v[0][e]))); v[0][e]=v[0][e]*cc[e]+sg*(p*sn[e]); }
;     }
;     #pragma unroll
;     for(int d0=0;d0<4;++d0){ u32x4 w; w[0]=cvtpk_s(v[d0][0]*QS,v[d0][1]*QS); w[1]=cvtpk_s(v[d0][2]*QS,v[d0][3]*QS); w[2]=cvtpk_s(v[d0][4]*QS,v[d0][5]*QS); w[3]=cvtpk_s(v[d0][6]*QS,v[d0][7]*QS);
;       qr[d0]=__builtin_bit_cast(bf16x8,w); }
;   }
;   WAIT_BAR(3);
;   qkt(pA0,pA1,Kbase+s0,qr,negm,r32,hi);asm volatile("s_nop 15\n\ts_nop 7":"+v"(pA0),"+v"(pA1));CMASK(pA0,pA1,0);
	v_mov_b32_e32 v28, v96
	v_mov_b32_e32 v29, v99
	v_mov_b32_e32 v91, v95
	s_waitcnt vmcnt(0)
	v_mov_b32_e32 v116, v100
	v_mov_b32_e32 v117, v103
	v_pk_mul_f32 v[50:51], v[50:51], v[88:89]
	v_pk_mul_f32 v[88:89], v[94:95], v[154:155] op_sel_hi:[0,1]
	v_mov_b32_e32 v26, v97
	v_mov_b32_e32 v27, v98
	v_pk_mul_f32 v[28:29], v[118:119], v[28:29]
	v_mov_b32_e32 v52, v101
	v_mov_b32_e32 v53, v102
	v_pk_mul_f32 v[88:89], v[90:91], v[88:89]
	v_pk_fma_f32 v[26:27], v[46:47], v[26:27], v[28:29]
	v_pk_mul_f32 v[28:29], v[50:51], v[116:117]
	v_mov_b32_e32 v107, v98
	v_pk_fma_f32 v[28:29], v[88:89], v[52:53], v[28:29]
	v_mov_b32_e32 v53, v119
	v_mov_b32_e32 v119, v47
	v_mov_b32_e32 v98, v97
	v_mov_b32_e32 v148, v84
	v_mov_b32_e32 v149, v59
	v_pk_mul_f32 v[90:91], v[94:95], v[144:145] op_sel_hi:[0,1]
	v_mov_b32_e32 v52, v46
	v_mov_b32_e32 v106, v96
	v_pk_mul_f32 v[46:47], v[118:119], v[98:99]
	v_mov_b32_e32 v59, v85
	v_mov_b32_e32 v150, v54
	v_mov_b32_e32 v151, v57
	v_pk_mul_f32 v[90:91], v[148:149], v[90:91]
	v_pk_mul_f32 v[48:49], v[94:95], v[48:49] op_sel_hi:[0,1]
	v_pk_fma_f32 v[46:47], v[52:53], v[106:107], v[46:47] neg_lo:[0,0,1] neg_hi:[0,0,1]
	v_mov_b32_e32 v130, v42
	v_mov_b32_e32 v131, v45
	v_mov_b32_e32 v84, v55
	v_mov_b32_e32 v85, v56
	v_pk_mul_f32 v[48:49], v[58:59], v[48:49]
	v_pk_mul_f32 v[30:31], v[90:91], v[150:151]
	v_pk_mul_f32 v[46:47], v[46:47], s[50:51] op_sel_hi:[1,0]
	v_pk_fma_f32 v[30:31], v[48:49], v[84:85], v[30:31]
	v_pk_mul_f32 v[84:85], v[76:77], v[130:131]
	v_cvt_pk_bf16_f32 v130, v46, v47
	v_mov_b32_e32 v47, v51
	v_mov_b32_e32 v53, v102
	v_mov_b32_e32 v51, v89
	v_mov_b32_e32 v102, v101
	v_mov_b32_e32 v46, v88
	v_mov_b32_e32 v52, v100
	v_pk_mul_f32 v[50:51], v[50:51], v[102:103]
	v_mov_b32_e32 v140, v86
	v_pk_fma_f32 v[46:47], v[46:47], v[52:53], v[50:51] neg_lo:[0,0,1] neg_hi:[0,0,1]
	v_mov_b32_e32 v51, v56
	v_pk_mul_f32 v[46:47], v[46:47], s[50:51] op_sel_hi:[1,0]
	v_mov_b32_e32 v56, v55
	v_cvt_pk_bf16_f32 v131, v46, v47
	v_mov_b32_e32 v47, v91
	v_mov_b32_e32 v91, v49
	v_mov_b32_e32 v46, v48
	v_mov_b32_e32 v50, v54
	v_pk_mul_f32 v[48:49], v[90:91], v[56:57]
	v_pk_mul_f32 v[58:59], v[94:95], v[132:133] op_sel_hi:[0,1]
	v_pk_fma_f32 v[46:47], v[46:47], v[50:51], v[48:49] neg_lo:[0,0,1] neg_hi:[0,0,1]
	v_mov_b32_e32 v142, v22
	v_mov_b32_e32 v143, v25
	v_pk_mul_f32 v[58:59], v[140:141], v[58:59]
	v_pk_mul_f32 v[46:47], v[46:47], s[50:51] op_sel_hi:[1,0]
	s_and_b32 s2, s2, 0x3fffffc0
	v_mov_b32_e32 v87, v24
	v_pk_mul_f32 v[32:33], v[58:59], v[142:143]
	v_cvt_pk_bf16_f32 v132, v46, v47
	v_mov_b32_e32 v47, v59
	v_mov_b32_e32 v49, v24
	v_mov_b32_e32 v59, v61
	v_mov_b32_e32 v24, v23
	s_lshl_b32 s2, s2, 2
	v_mov_b32_e32 v86, v23
	v_mov_b32_e32 v46, v60
	v_mov_b32_e32 v48, v22
	v_pk_mul_f32 v[22:23], v[58:59], v[24:25]
	s_add_i32 s25, s2, 0
	v_pk_fma_f32 v[22:23], v[46:47], v[48:49], v[22:23] neg_lo:[0,0,1] neg_hi:[0,0,1]
	s_add_i32 s25, s25, 0x12000
	v_pk_mul_f32 v[22:23], v[22:23], s[50:51] op_sel_hi:[1,0]
	s_and_b64 s[4:5], s[6:7], exec
	v_cvt_pk_bf16_f32 v133, v22, v23
	v_pk_mul_f32 v[22:23], v[26:27], s[50:51] op_sel_hi:[1,0]
	v_lshlrev_b32_e32 v164, 10, v206
	v_lshlrev_b32_e32 v165, 4, v205
	s_cselect_b32 s24, 0x80, 64
	v_cvt_pk_bf16_f32 v122, v22, v23
	v_pk_mul_f32 v[22:23], v[28:29], s[50:51] op_sel_hi:[1,0]
	s_add_i32 s2, s20, 0
	v_pk_fma_f32 v[32:33], v[60:61], v[86:87], v[32:33]
	v_cvt_pk_bf16_f32 v123, v22, v23
	v_pk_mul_f32 v[22:23], v[30:31], s[50:51] op_sel_hi:[1,0]
	s_waitcnt vmcnt(3) lgkmcnt(0)
	s_barrier
	v_add3_u32 v1, s2, v164, v165
	v_mov_b32_e32 v80, v18
	v_mov_b32_e32 v81, v21
	v_cvt_pk_bf16_f32 v124, v22, v23
	v_pk_mul_f32 v[22:23], v[32:33], s[50:51] op_sel_hi:[1,0]
	ds_read_b128 v[46:49], v1 offset:512
	ds_read_b128 v[50:53], v1
	v_mov_b32_e32 v69, v20
	v_pk_mul_f32 v[80:81], v[82:83], v[80:81]
	v_cvt_pk_bf16_f32 v125, v22, v23
	v_mov_b32_e32 v23, v83
	v_mov_b32_e32 v25, v20
	v_mov_b32_e32 v83, v93
	v_mov_b32_e32 v20, v19
	v_mov_b32_e32 v68, v19
	v_mov_b32_e32 v22, v92
	v_mov_b32_e32 v24, v18
	v_pk_mul_f32 v[18:19], v[82:83], v[20:21]
	v_mov_b32_e32 v67, v44
	v_pk_fma_f32 v[18:19], v[22:23], v[24:25], v[18:19] neg_lo:[0,0,1] neg_hi:[0,0,1]
	v_mov_b32_e32 v55, v77
	v_pk_mul_f32 v[18:19], v[18:19], s[50:51] op_sel_hi:[1,0]
	v_mov_b32_e32 v57, v44
	v_mov_b32_e32 v77, v109
	v_mov_b32_e32 v44, v43
	v_mov_b32_e32 v66, v43
	v_cvt_pk_bf16_f32 v138, v18, v19
	v_mov_b32_e32 v54, v108
	v_mov_b32_e32 v56, v42
	s_waitcnt lgkmcnt(0)
	v_mfma_f32_32x32x16_bf16 v[18:33], v[50:53], v[130:133], v[2:17]
	v_mul_f32_e64 v42, v76, v44
	v_mul_f32_e64 v43, v77, v45
	v_mov_b32_e32 v128, v38
	v_fma_f32 v42, v54, v56, -v42
	v_fma_f32 v43, v55, v57, -v43
	v_mov_b32_e32 v129, v41
	v_pk_mul_f32 v[42:43], v[42:43], s[50:51] op_sel_hi:[1,0]
	v_mov_b32_e32 v65, v40
	v_cvt_pk_bf16_f32 v139, v42, v43
	v_mfma_f32_32x32x16_bf16 v[2:17], v[46:49], v[130:133], v[2:17]
	ds_read_b128 v[42:45], v1 offset:2560
	ds_read_b128 v[50:53], v1 offset:2048
	v_mul_f32_e64 v86, v78, v128
	v_mul_f32_e64 v87, v79, v129
	v_mov_b32_e32 v55, v79
	v_mov_b32_e32 v47, v40
	v_mov_b32_e32 v79, v105
	v_mov_b32_e32 v40, v39
	v_mov_b32_e32 v64, v39
	v_mov_b32_e32 v54, v104
	v_mov_b32_e32 v46, v38
	v_pk_mul_f32 v[38:39], v[78:79], v[40:41]
	s_waitcnt lgkmcnt(0)
; __device__ __forceinline__ float max3f(float a,float b,float c){float r;asm("v_max3_f32 %0, %1, %2, %3":"=v"(r):"v"(a),"v"(b),"v"(c));return r;}
; __device__ __forceinline__ float max2f(float a,float b){float r;asm("v_max_f32_e32 %0, %1, %2":"=v"(r):"v"(a),"v"(b));return r;}
; #define WAIT_BAR(N) asm volatile("s_waitcnt vmcnt(" #N ") lgkmcnt(0)\n\ts_barrier":::"memory")
;   #define DMA_K(t,slot) glds16(ksrc+(long)(t)*KVBLK*DM,(unsigned)__builtin_amdgcn_readfirstlane(kdst+(slot)))
;   #define DMA_V(t,slot) do{ glds16(vsrc+(long)(t)*KVBLK*DM,(unsigned)__builtin_amdgcn_readfirstlane(vdst+VM*(slot))); \
;     if constexpr(DV==128){ glds16(vsrc+64+(long)(t)*KVBLK*DM,(unsigned)__builtin_amdgcn_readfirstlane(vdst+VM*(slot)+8192)); } }while(0)
;   #define WAIT_KV() do{ if constexpr(DV==128){WAIT_BAR(3);} else {WAIT_BAR(2);} }while(0)
;   #define CMASK(P0,P1,t) do{ if constexpr(WIN){ wmask(P0,P1,(t_lo+(t))*KVBLK+4*hi,qpos); } }while(0)
;   #define ROT() do{sl_prev=sl_cur;sl_cur=sl_next;sl_next=(sl_next==(NSLOT-1)*SLOTB)?0:sl_next+SLOTB;}while(0)
; __device__ __forceinline__ float rowmax(const f32x16&p0,const f32x16&p1){
;   float a=max3f(p0[0],p0[1],p1[0]),b=max3f(p0[2],p0[3],p1[1]);a=max3f(a,p1[2],p1[3]);
;   #pragma unroll
;   for(int r=4;r<16;r+=4){a=max3f(a,p0[r],p0[r+1]);b=max3f(b,p0[r+2],p0[r+3]);a=max3f(a,p1[r],p1[r+1]);b=max3f(b,p1[r+2],p1[r+3]);}
;   const float m=max2f(a,b);
;   auto rr=__builtin_amdgcn_permlane32_swap(__float_as_uint(m),__float_as_uint(m),false,false);
;   return max2f(__uint_as_float(rr[0]),__uint_as_float(rr[1]));
; template<int THRL,bool WIN,int DM,int ODM,int DV,int QMODE> __device__ __forceinline__ void attn_unit(const bf16*Qp,const bf16*__restrict__ Kp,const bf16*__restrict__ Vp,bf16*Op,const int q0,const int t_lo,const int NT,const float sink2,char*shm,const float*qgain,const float*qtab,const int b0,const ...
;     ...
;   WAIT_BAR(3);
;   qkt(pA0,pA1,Kbase+s0,qr,negm,r32,hi);asm volatile("s_nop 15\n\ts_nop 7":"+v"(pA0),"+v"(pA1));CMASK(pA0,pA1,0);
;   START(pA0,pA1);
;   _Pragma("unroll") for(int r=0;r<16;++r)pA1[r]=__builtin_amdgcn_exp2f(pA1[r]);
;   WAIT_BAR(0);
;   DMA_K(3,s0);DMA_V(1,s1);
;   ROT();
;   kload8(kf,kp0+sl_cur);
;   WAIT_KV();
	v_mfma_f32_32x32x16_bf16 v[18:33], v[50:53], v[122:125], v[18:33]
	v_fma_f32 v38, v54, v46, -v38
	v_fma_f32 v39, v55, v47, -v39
	v_mov_b32_e32 v126, v34
	v_mov_b32_e32 v127, v37
	v_mul_f32_e64 v38, v38, s50
	v_mul_f32_e64 v39, v39, s50
	v_mov_b32_e32 v63, v36
	v_pk_mul_f32 v[94:95], v[70:71], v[126:127]
	v_cvt_pk_bf16_f32 v140, v38, v39
	v_mfma_f32_32x32x16_bf16 v[2:17], v[42:45], v[122:125], v[2:17]
	v_mov_b32_e32 v51, v71
	ds_read_b128 v[38:41], v1 offset:4608
	ds_read_b128 v[46:49], v1 offset:4096
	v_mov_b32_e32 v53, v36
	v_mov_b32_e32 v71, v73
	v_mov_b32_e32 v36, v35
	v_mov_b32_e32 v62, v35
	v_mov_b32_e32 v50, v72
	v_mov_b32_e32 v52, v34
	v_pk_mul_f32 v[34:35], v[70:71], v[36:37]
	v_lshlrev_b32_e32 v75, 1, v74
	v_pk_fma_f32 v[34:35], v[50:51], v[52:53], v[34:35] neg_lo:[0,0,1] neg_hi:[0,0,1]
	v_pk_fma_f32 v[50:51], v[72:73], v[62:63], v[94:95]
	v_pk_mul_f32 v[34:35], v[34:35], s[50:51] op_sel_hi:[1,0]
	v_and_b32_e32 v195, 32, v75
	v_cvt_pk_bf16_f32 v141, v34, v35
	v_pk_fma_f32 v[34:35], v[92:93], v[68:69], v[80:81]
	v_add3_u32 v211, 0, v164, v165
	s_waitcnt lgkmcnt(0)
	v_mfma_f32_32x32x16_bf16 v[18:33], v[46:49], v[138:141], v[18:33]
	v_fma_f32 v46, v108, v66, v84
	v_fma_f32 v47, v109, v67, v85
	v_mul_f32_e64 v52, v34, s50
	v_mul_f32_e64 v53, v35, s50
	ds_read_b128 v[34:37], v1 offset:6656
	ds_read_b128 v[42:45], v1 offset:6144
	v_pk_fma_f32 v[48:49], v[104:105], v[64:65], v[86:87]
	v_lshlrev_b32_e32 v1, 4, v74
	v_cvt_pk_bf16_f32 v134, v52, v53
	v_and_b32_e32 v1, 0xc0, v1
	v_mfma_f32_32x32x16_bf16 v[2:17], v[38:41], v[138:141], v[2:17]
	v_mul_f32_e64 v38, v46, s50
	v_mul_f32_e64 v39, v47, s50
	v_lshl_or_b32 v207, v206, 8, v1
	v_cvt_pk_bf16_f32 v135, v38, v39
	v_mul_f32_e64 v38, v48, s50
	v_mul_f32_e64 v39, v49, s50
	v_add_u32_e32 v1, 0, v195
	v_cvt_pk_bf16_f32 v136, v38, v39
	v_pk_mul_f32 v[38:39], v[50:51], s[50:51] op_sel_hi:[1,0]
	v_add3_u32 v210, v1, v191, v207
	v_cvt_pk_bf16_f32 v137, v38, v39
	s_add_i32 s2, s22, s20
	s_mov_b32 s13, 1
	s_waitcnt lgkmcnt(0)
	v_mfma_f32_32x32x16_bf16 v[18:33], v[42:45], v[134:137], v[18:33]
	s_mov_b32 s26, 5
	s_add_i32 s15, s24, -5
	v_lshl_add_u32 v208, v205, 2, s25
	v_lshl_add_u64 v[182:183], v[198:199], 0, s[56:57]
	v_lshl_add_u64 v[184:185], v[196:197], 0, s[58:59]
	v_lshl_add_u64 v[200:201], v[198:199], 0, s[60:61]
	v_mov_b32_e32 v212, 0
	v_mfma_f32_32x32x16_bf16 v[2:17], v[34:37], v[134:137], v[2:17]
	s_nop 15
	s_nop 7
	s_nop 0
	v_max3_f32 v1, v18, v19, v2
	v_max3_f32 v34, v20, v21, v3
	s_nop 0
	v_max3_f32 v1, v1, v4, v5
	v_max3_f32 v34, v34, v24, v25
	s_nop 0
	v_max3_f32 v1, v1, v22, v23
	v_max3_f32 v34, v34, v8, v9
	s_nop 0
	v_max3_f32 v1, v1, v6, v7
	v_max3_f32 v34, v34, v28, v29
	s_nop 0
	v_max3_f32 v1, v1, v26, v27
	v_max3_f32 v34, v34, v12, v13
	s_nop 0
	v_max3_f32 v1, v1, v10, v11
	v_max3_f32 v34, v34, v32, v33
	s_nop 0
	v_max3_f32 v1, v1, v30, v31
	v_max3_f32 v34, v34, v16, v17
	s_nop 0
	v_max3_f32 v1, v1, v14, v15
	s_nop 0
	v_max_f32_e32 v1, v1, v34
	s_nop 0
	v_mov_b32_e32 v34, v1
	s_nop 1
	v_permlane32_swap_b32_e32 v1, v34
	v_max_f32_e32 v1, v1, v34
	s_nop 0
	v_add_f32_e32 v209, v0, v1
	v_sub_f32_e32 v50, v2, v1
	v_sub_f32_e32 v51, v3, v1
	v_lshl_add_u64 v[2:3], v[196:197], 0, s[56:57]
	v_xor_b32_e32 v34, 0x80000000, v209
	v_mov_b32_e32 v35, v34
	v_mov_b32_e32 v36, v34
	v_mov_b32_e32 v37, v34
	v_mov_b32_e32 v38, v34
	v_mov_b32_e32 v39, v34
	v_mov_b32_e32 v40, v34
	v_mov_b32_e32 v41, v34
	v_mov_b32_e32 v42, v34
	v_mov_b32_e32 v43, v34
	v_mov_b32_e32 v44, v34
	v_mov_b32_e32 v45, v34
	v_mov_b32_e32 v46, v34
	v_mov_b32_e32 v47, v34
	v_mov_b32_e32 v48, v34
	v_mov_b32_e32 v49, v34
	s_waitcnt vmcnt(0) lgkmcnt(0)
	s_barrier
	s_mov_b32 s4, m0
	s_mov_b32 m0, s2
	s_nop 0
	global_load_lds_dwordx4 v[2:3], off
	s_mov_b32 m0, s4
	v_lshl_add_u64 v[2:3], v[198:199], 0, s[54:55]
	s_add_i32 s2, s23, s3
	s_mov_b32 s4, m0
	s_mov_b32 m0, s2
	s_nop 0
	global_load_lds_dwordx4 v[2:3], off
	s_mov_b32 m0, s4
	v_add_u32_e32 v2, s3, v211
	ds_read_b128 v[174:177], v2
	ds_read_b128 v[170:173], v2 offset:512
	ds_read_b128 v[166:169], v2 offset:2048
	ds_read_b128 v[162:165], v2 offset:2560
	ds_read_b128 v[158:161], v2 offset:4096
	ds_read_b128 v[154:157], v2 offset:4608
	ds_read_b128 v[150:153], v2 offset:6144
	ds_read_b128 v[146:149], v2 offset:6656
	v_sub_f32_e32 v18, v18, v1
	v_sub_f32_e32 v19, v19, v1
	v_sub_f32_e32 v20, v20, v1
	v_sub_f32_e32 v4, v4, v1
	v_sub_f32_e32 v21, v21, v1
	v_sub_f32_e32 v5, v5, v1
	v_sub_f32_e32 v22, v22, v1
	v_sub_f32_e32 v6, v6, v1
	v_sub_f32_e32 v23, v23, v1
	v_sub_f32_e32 v7, v7, v1
	v_sub_f32_e32 v24, v24, v1
	v_sub_f32_e32 v8, v8, v1
	v_sub_f32_e32 v25, v25, v1
	v_sub_f32_e32 v9, v9, v1
	v_sub_f32_e32 v26, v26, v1
	v_sub_f32_e32 v10, v10, v1
	v_sub_f32_e32 v27, v27, v1
	v_sub_f32_e32 v11, v11, v1
	v_sub_f32_e32 v28, v28, v1
	v_sub_f32_e32 v12, v12, v1
	v_sub_f32_e32 v29, v29, v1
	v_sub_f32_e32 v13, v13, v1
	v_sub_f32_e32 v30, v30, v1
	v_sub_f32_e32 v14, v14, v1
	v_sub_f32_e32 v31, v31, v1
	v_sub_f32_e32 v15, v15, v1
	v_sub_f32_e32 v32, v32, v1
	v_sub_f32_e32 v16, v16, v1
	v_sub_f32_e32 v33, v33, v1
	v_sub_f32_e32 v1, v17, v1
	s_nop 0
	v_exp_f32_e32 v66, v18
	v_exp_f32_e32 v81, v33
	v_exp_f32_e32 v67, v19
	v_exp_f32_e32 v68, v20
	v_exp_f32_e32 v69, v21
	v_exp_f32_e32 v70, v22
	v_exp_f32_e32 v71, v23
	v_exp_f32_e32 v72, v24
	v_exp_f32_e32 v73, v25
	v_exp_f32_e32 v74, v26
	v_exp_f32_e32 v75, v27
	v_exp_f32_e32 v76, v28
	v_exp_f32_e32 v77, v29
	v_exp_f32_e32 v78, v30
	v_exp_f32_e32 v79, v31
	v_exp_f32_e32 v80, v32
	v_exp_f32_e32 v65, v1
	v_exp_f32_e32 v50, v50
	v_exp_f32_e32 v51, v51
	v_exp_f32_e32 v52, v4
	v_exp_f32_e32 v53, v5
	v_exp_f32_e32 v54, v6
	v_exp_f32_e32 v55, v7
	v_exp_f32_e32 v56, v8
	v_exp_f32_e32 v57, v9
	v_exp_f32_e32 v58, v10
	v_exp_f32_e32 v59, v11
	v_exp_f32_e32 v60, v12
	v_exp_f32_e32 v61, v13
	v_exp_f32_e32 v62, v14
	v_exp_f32_e32 v63, v15
	v_exp_f32_e32 v64, v16
	s_waitcnt vmcnt(2) lgkmcnt(0)
	s_barrier
	v_mov_b32_e32 v2, v0
	v_mov_b32_e32 v3, v0
	v_mov_b32_e32 v4, v0
	v_mov_b32_e32 v5, v0
	v_mov_b32_e32 v6, v0
	v_mov_b32_e32 v7, v0
	v_mov_b32_e32 v8, v0
	v_mov_b32_e32 v9, v0
	v_mov_b32_e32 v10, v0
	v_mov_b32_e32 v11, v0
	v_mov_b32_e32 v12, v0
	v_mov_b32_e32 v13, v0
	v_mov_b32_e32 v14, v0
	v_mov_b32_e32 v15, v0
	v_mov_b32_e32 v16, v0
	v_mov_b32_e32 v17, v0
	v_mov_b32_e32 v18, v0
	v_mov_b32_e32 v19, v0
	v_mov_b32_e32 v20, v0
	v_mov_b32_e32 v21, v0
	v_mov_b32_e32 v22, v0
	v_mov_b32_e32 v23, v0
	v_mov_b32_e32 v24, v0
	v_mov_b32_e32 v25, v0
	v_mov_b32_e32 v26, v0
	v_mov_b32_e32 v27, v0
	v_mov_b32_e32 v28, v0
	v_mov_b32_e32 v29, v0
	v_mov_b32_e32 v30, v0
	v_mov_b32_e32 v31, v0
	v_mov_b32_e32 v1, v0
	v_mov_b64_e32 v[32:33], v[30:31]
	v_cmp_gt_u32_e64 s[4:5], 32, v203
	v_mov_b64_e32 v[30:31], v[28:29]
	v_mov_b64_e32 v[28:29], v[26:27]
	v_mov_b64_e32 v[26:27], v[24:25]
	v_mov_b64_e32 v[24:25], v[22:23]
	v_mov_b64_e32 v[22:23], v[20:21]
	v_mov_b64_e32 v[20:21], v[18:19]
	v_mov_b64_e32 v[18:19], v[16:17]
	v_mov_b64_e32 v[16:17], v[14:15]
	v_mov_b64_e32 v[14:15], v[12:13]
	v_mov_b64_e32 v[12:13], v[10:11]
	v_mov_b64_e32 v[10:11], v[8:9]
	v_mov_b64_e32 v[8:9], v[6:7]
	v_mov_b64_e32 v[6:7], v[4:5]
	v_mov_b64_e32 v[4:5], v[2:3]
	v_mov_b64_e32 v[2:3], v[0:1]
	v_readfirstlane_b32 s98, v182
	v_readfirstlane_b32 s99, v183
	s_mov_b64 s[100:101], 0
	s_nop 0
	v_subrev_u32_e32 v215, s98, v182
	v_subrev_u32_e32 v213, s98, v184
	v_add_u32_e32 v216, 0x48000, v215
	v_add_u32_e32 v214, 0x48000, v213
	s_add_u32 s98, s98, s62
	s_addc_u32 s99, s99, s63
.LBB0_383:
	v_add_u32_e32 v1, s20, v210
	ds_read_b64_tr_b16 v[178:179], v1 offset:24576
	ds_read_b64_tr_b16 v[180:181], v1 offset:25088
	s_waitcnt lgkmcnt(9)
	v_mfma_f32_32x32x16_bf16 v[98:113], v[174:177], v[130:133], v[34:49]
	v_add_f32_e32 v82, v66, v67
	v_add_f32_e32 v82, v68, v82
	v_add_f32_e32 v82, v69, v82
	v_add_f32_e32 v82, v70, v82
	v_add_f32_e32 v82, v71, v82
	v_cvt_pk_bf16_f32 v142, v66, v67
	v_cvt_pk_bf16_f32 v143, v68, v69
	ds_read_b64_tr_b16 v[174:175], v1 offset:28672
	ds_read_b64_tr_b16 v[176:177], v1 offset:29184
	v_add_f32_e32 v66, v72, v82
	s_waitcnt lgkmcnt(10)
	v_mfma_f32_32x32x16_bf16 v[82:97], v[170:173], v[130:133], v[34:49]
	v_add_f32_e32 v66, v73, v66
	v_add_f32_e32 v66, v74, v66
	v_add_f32_e32 v114, v75, v66
	v_cvt_pk_bf16_f32 v144, v70, v71
	v_cvt_pk_bf16_f32 v145, v72, v73
	ds_read_b64_tr_b16 v[66:67], v1 offset:25600
	ds_read_b64_tr_b16 v[68:69], v1 offset:26112
	s_waitcnt lgkmcnt(11)
	v_mfma_f32_32x32x16_bf16 v[98:113], v[166:169], v[122:125], v[98:113]
	v_add_f32_e32 v70, v76, v114
	v_add_f32_e32 v70, v77, v70
	v_add_f32_e32 v70, v78, v70
	v_add_f32_e32 v114, v79, v70
	v_cvt_pk_bf16_f32 v126, v74, v75
	v_cvt_pk_bf16_f32 v127, v76, v77
	ds_read_b64_tr_b16 v[70:71], v1 offset:29696
	ds_read_b64_tr_b16 v[72:73], v1 offset:30208
	s_waitcnt lgkmcnt(12)
	v_mfma_f32_32x32x16_bf16 v[82:97], v[162:165], v[122:125], v[82:97]
	v_add_f32_e32 v74, v80, v114
	v_add_f32_e32 v74, v81, v74
	v_add_f32_e32 v74, v50, v74
	v_add_f32_e32 v114, v51, v74
	v_cvt_pk_bf16_f32 v128, v78, v79
	v_cvt_pk_bf16_f32 v129, v80, v81
	ds_read_b64_tr_b16 v[74:75], v1 offset:26624
	ds_read_b64_tr_b16 v[76:77], v1 offset:27136
	s_waitcnt lgkmcnt(13)
	v_mfma_f32_32x32x16_bf16 v[98:113], v[158:161], v[138:141], v[98:113]
	v_add_f32_e32 v78, v52, v114
	v_add_f32_e32 v78, v53, v78
	v_add_f32_e32 v78, v54, v78
	v_add_f32_e32 v78, v55, v78
	v_cvt_pk_bf16_f32 v118, v50, v51
	v_cvt_pk_bf16_f32 v119, v52, v53
	ds_read_b64_tr_b16 v[50:51], v1 offset:30720
	ds_read_b64_tr_b16 v[52:53], v1 offset:31232
	s_waitcnt lgkmcnt(14)
	v_mfma_f32_32x32x16_bf16 v[82:97], v[154:157], v[138:141], v[82:97]
	v_add_f32_e32 v78, v56, v78
	v_add_f32_e32 v78, v57, v78
	v_add_f32_e32 v78, v58, v78
	v_add_f32_e32 v78, v59, v78
	v_cvt_pk_bf16_f32 v120, v54, v55
	v_cvt_pk_bf16_f32 v121, v56, v57
	ds_read_b64_tr_b16 v[54:55], v1 offset:27648
	ds_read_b64_tr_b16 v[56:57], v1 offset:28160
	s_waitcnt lgkmcnt(14)
	v_mfma_f32_32x32x16_bf16 v[98:113], v[150:153], v[134:137], v[98:113]
	v_add_f32_e32 v78, v60, v78
	v_add_f32_e32 v78, v61, v78
	v_add_f32_e32 v78, v62, v78
	v_add_f32_e32 v78, v63, v78
	v_cvt_pk_bf16_f32 v114, v58, v59
	v_cvt_pk_bf16_f32 v115, v60, v61
	ds_read_b64_tr_b16 v[58:59], v1 offset:31744
	ds_read_b64_tr_b16 v[60:61], v1 offset:32256
	v_mfma_f32_32x32x16_bf16 v[82:97], v[146:149], v[134:137], v[82:97]
	v_add_f32_e32 v1, v64, v78
	v_add_f32_e32 v1, v65, v1
	v_cvt_pk_bf16_f32 v116, v62, v63
	v_cvt_pk_bf16_f32 v117, v64, v65
	s_add_i32 s2, s3, s22
	s_mov_b32 s6, m0
	s_mov_b32 m0, s2
	s_nop 0
	global_load_lds_dwordx4 v213, s[98:99]
	s_mov_b32 m0, s6
	s_add_i32 s2, s27, s23
	s_mov_b32 s6, m0
	s_mov_b32 m0, s2
	s_nop 0
	global_load_lds_dwordx4 v215, s[98:99]
	s_mov_b32 m0, s6
	v_max_f32_e32 v62, v98, v99
	v_max3_f32 v63, v100, v101, v83
	v_max3_f32 v62, v62, v82, v84
	v_max3_f32 v62, v62, v85, v102
	v_max3_f32 v63, v63, v104, v105
	v_max3_f32 v62, v62, v103, v86
	v_max3_f32 v63, v63, v88, v89
	v_max3_f32 v62, v62, v87, v106
	v_max3_f32 v63, v63, v108, v109
	v_max3_f32 v62, v62, v107, v90
	v_max3_f32 v63, v63, v92, v93
	v_max3_f32 v62, v62, v91, v110
	v_max3_f32 v63, v63, v112, v113
	v_max3_f32 v62, v62, v111, v94
	v_max3_f32 v63, v63, v96, v97
	v_max3_f32 v62, v62, v95, v63
	v_cmp_lt_f32_e32 vcc, s19, v62
	s_cmp_lg_u64 vcc, 0
	v_add_f32_e32 v1, v212, v1
	s_cselect_b64 s[6:7], -1, 0
	s_cbranch_vccnz .LBB0_391

.LBB0_386:
	s_add_i32 s2, s27, 0x2000
	s_cmpk_lg_i32 s27, 0x4000
	s_cselect_b32 s14, s2, 0
	v_add_u32_e32 v186, s3, v210
	ds_read_b64_tr_b16 v[150:151], v186 offset:24576
	ds_read_b64_tr_b16 v[152:153], v186 offset:25088
	s_waitcnt lgkmcnt(9)
	v_mfma_f32_32x32x16_bf16 v[66:81], v[62:65], v[130:133], v[34:49]
	v_add_f32_e32 v50, v98, v99
	v_add_f32_e32 v50, v100, v50
	v_add_f32_e32 v50, v101, v50
	v_add_f32_e32 v50, v102, v50
	v_add_f32_e32 v50, v103, v50
	v_cvt_pk_bf16_f32 v142, v98, v99
	v_cvt_pk_bf16_f32 v143, v100, v101
	ds_read_b64_tr_b16 v[146:147], v186 offset:28672
	ds_read_b64_tr_b16 v[148:149], v186 offset:29184
	v_add_f32_e32 v50, v104, v50
	v_add_f32_e32 v50, v105, v50
	v_add_f32_e32 v50, v106, v50
	v_add_f32_e32 v114, v107, v50
	s_waitcnt lgkmcnt(10)
	v_mfma_f32_32x32x16_bf16 v[50:65], v[174:177], v[130:133], v[34:49]
	v_cvt_pk_bf16_f32 v144, v102, v103
	v_cvt_pk_bf16_f32 v145, v104, v105
	ds_read_b64_tr_b16 v[98:99], v186 offset:25600
	ds_read_b64_tr_b16 v[100:101], v186 offset:26112
	s_waitcnt lgkmcnt(11)
	v_mfma_f32_32x32x16_bf16 v[66:81], v[178:181], v[122:125], v[66:81]
	v_add_f32_e32 v102, v108, v114
	v_add_f32_e32 v102, v109, v102
	v_add_f32_e32 v102, v110, v102
	v_add_f32_e32 v114, v111, v102
	v_cvt_pk_bf16_f32 v126, v106, v107
	v_cvt_pk_bf16_f32 v127, v108, v109
	ds_read_b64_tr_b16 v[102:103], v186 offset:29696
	ds_read_b64_tr_b16 v[104:105], v186 offset:30208
	s_waitcnt lgkmcnt(12)
	v_mfma_f32_32x32x16_bf16 v[50:65], v[170:173], v[122:125], v[50:65]
	v_add_f32_e32 v106, v112, v114
	v_add_f32_e32 v106, v113, v106
	v_add_f32_e32 v106, v82, v106
	v_add_f32_e32 v114, v83, v106
	v_cvt_pk_bf16_f32 v128, v110, v111
	v_cvt_pk_bf16_f32 v129, v112, v113
	ds_read_b64_tr_b16 v[106:107], v186 offset:26624
	ds_read_b64_tr_b16 v[108:109], v186 offset:27136
	s_waitcnt lgkmcnt(13)
	v_mfma_f32_32x32x16_bf16 v[66:81], v[166:169], v[138:141], v[66:81]
	v_add_f32_e32 v110, v84, v114
	v_add_f32_e32 v110, v85, v110
	v_add_f32_e32 v110, v86, v110
	v_add_f32_e32 v110, v87, v110
	v_cvt_pk_bf16_f32 v118, v82, v83
	v_cvt_pk_bf16_f32 v119, v84, v85
	ds_read_b64_tr_b16 v[82:83], v186 offset:30720
	ds_read_b64_tr_b16 v[84:85], v186 offset:31232
	s_waitcnt lgkmcnt(14)
	v_mfma_f32_32x32x16_bf16 v[50:65], v[162:165], v[138:141], v[50:65]
	v_add_f32_e32 v110, v88, v110
	v_add_f32_e32 v110, v89, v110
	v_add_f32_e32 v110, v90, v110
	v_add_f32_e32 v110, v91, v110
	v_cvt_pk_bf16_f32 v120, v86, v87
	v_cvt_pk_bf16_f32 v121, v88, v89
	ds_read_b64_tr_b16 v[86:87], v186 offset:27648
	ds_read_b64_tr_b16 v[88:89], v186 offset:28160
	s_waitcnt lgkmcnt(14)
	v_mfma_f32_32x32x16_bf16 v[66:81], v[158:161], v[134:137], v[66:81]
	v_add_f32_e32 v110, v92, v110
	v_add_f32_e32 v110, v93, v110
	v_add_f32_e32 v110, v94, v110
	v_add_f32_e32 v110, v95, v110
	v_cvt_pk_bf16_f32 v114, v90, v91
	v_cvt_pk_bf16_f32 v115, v92, v93
	ds_read_b64_tr_b16 v[90:91], v186 offset:31744
	ds_read_b64_tr_b16 v[92:93], v186 offset:32256
	v_mfma_f32_32x32x16_bf16 v[50:65], v[154:157], v[134:137], v[50:65]
	v_add_f32_e32 v110, v96, v110
	v_add_f32_e32 v110, v97, v110
	v_cvt_pk_bf16_f32 v116, v94, v95
	v_cvt_pk_bf16_f32 v117, v96, v97
	v_max_f32_e32 v94, v66, v67
	s_nop 6
	v_max3_f32 v95, v68, v69, v51
	v_max3_f32 v94, v94, v50, v52
	v_max3_f32 v94, v94, v53, v70
	v_max3_f32 v95, v95, v72, v73
	v_max3_f32 v94, v94, v71, v54
	v_max3_f32 v95, v95, v56, v57
	v_max3_f32 v94, v94, v55, v74
	v_max3_f32 v95, v95, v76, v77
	v_max3_f32 v94, v94, v75, v58
	v_max3_f32 v95, v95, v60, v61
	v_max3_f32 v94, v94, v59, v78
	v_max3_f32 v95, v95, v80, v81
	v_max3_f32 v94, v94, v79, v62
	v_max3_f32 v95, v95, v64, v65
	v_add_f32_e32 v212, v1, v110
	v_max3_f32 v1, v94, v63, v95
	s_add_i32 s2, s27, s22
	s_mov_b32 s3, m0
	s_mov_b32 m0, s2
	s_nop 0
	global_load_lds_dwordx4 v214, s[98:99]
	s_mov_b32 m0, s3
	s_add_i32 s2, s14, s23
	s_mov_b32 s3, m0
	s_mov_b32 m0, s2
	s_nop 0
	global_load_lds_dwordx4 v216, s[98:99]
	s_mov_b32 m0, s3
	v_cmp_lt_f32_e32 vcc, s19, v1
	s_cmp_lg_u64 vcc, 0
	s_cselect_b64 s[6:7], -1, 0
	s_cbranch_vccnz .LBB0_394

;   #define WAIT_KV() do{ if constexpr(DV==128){WAIT_BAR(3);} else {WAIT_BAR(2);} }while(0)
;   #define RESC() do{ if(resc){ asm volatile("s_waitcnt lgkmcnt(0)":::"memory"); \
;       _Pragma("unroll") for(int d_=0;d_<DV/32;++d_) _Pragma("unroll") for(int r=0;r<16;++r)o[d_][r]*=wsf[crow(r,hi)]; } }while(0)
;   #define ROT() do{sl_prev=sl_cur;sl_cur=sl_next;sl_next=(sl_next==(NSLOT-1)*SLOTB)?0:sl_next+SLOTB;}while(0)
; template<int THRL,bool WIN,int DM,int ODM,int DV,int QMODE> __device__ __forceinline__ void attn_unit(const bf16*Qp,const bf16*__restrict__ Kp,const bf16*__restrict__ Vp,bf16*Op,const int q0,const int t_lo,const int NT,const float sink2,char*shm,const float*qgain,const float*qtab,const int b0,const ...
;     ...
;   int t=1;
;   for(;t+5<NT;t+=2){
;     STEP(pB0,pB1,pA0,pA1,t,true,true,true);     WAIT_KV(); RESC(); ROT();
;     STEP(pA0,pA1,pB0,pB1,t+1,true,true,true);   WAIT_KV(); RESC(); ROT();
;   }
.LBB0_389:
	s_add_i32 s13, s13, 2
	s_add_i32 s2, s14, 0x2000
	s_cmpk_lg_i32 s14, 0x4000
	s_cselect_b32 s2, s2, 0
	s_add_i32 s3, s26, 2
	s_add_u32 s98, s98, 0x90000
	s_addc_u32 s99, s99, 0
	s_add_u32 s100, s100, 0x90000
	s_addc_u32 s101, s101, 0
	s_cmp_ge_u32 s13, s15
	s_cbranch_scc1 .Lmy_a_exit
	s_mov_b32 s26, s3
	s_mov_b32 s20, s27
	s_mov_b32 s3, s14
	s_mov_b32 s27, s2
	s_branch .LBB0_383
.Lmy_a_exit:
	v_lshl_add_u64 v[182:183], v[182:183], 0, s[100:101]
	v_lshl_add_u64 v[184:185], v[184:185], 0, s[100:101]
	s_sub_u32 s100, s100, 0x90000
	s_subb_u32 s101, s101, 0
	v_lshl_add_u64 v[200:201], v[200:201], 0, s[100:101]
	s_branch .LBB0_397

; __device__ __forceinline__ unsigned cvtpk_s(float lo,float hi){f32x2_t v={lo,hi};bf16x2_t b=__builtin_convertvector(v,bf16x2_t);return __builtin_bit_cast(unsigned,b);}
; #define WAIT_BAR(N) asm volatile("s_waitcnt vmcnt(" #N ") lgkmcnt(0)\n\ts_barrier":::"memory")
;   #define CMASK(P0,P1,t) do{ if constexpr(WIN){ wmask(P0,P1,(t_lo+(t))*KVBLK+4*hi,qpos); } }while(0)
; template<int THRL,bool WIN,int DM,int ODM,int DV,int QMODE> __device__ __forceinline__ void attn_unit(const bf16*Qp,const bf16*__restrict__ Kp,const bf16*__restrict__ Vp,bf16*Op,const int q0,const int t_lo,const int NT,const float sink2,char*shm,const float*qgain,const float*qtab,const int b0,const ...
;     ...
;       const float*tb=qtab+(size_t)qpos*16;
;       const f32x4_t c0=*(const f32x4_t*)(tb),c1=*(const f32x4_t*)(tb+4),c2=*(const f32x4_t*)(tb+8),c3=*(const f32x4_t*)(tb+12);
;       const float cc[8]={c0.x,c0.z,c1.x,c1.z,c2.x,c2.z,c3.x,c3.z},sn[8]={c0.y,c0.w,c1.y,c1.w,c2.y,c2.w,c3.y,c3.w};
;       const float sg=hi?1.f:-1.f;
;       #pragma unroll
;       for(int e=0;e<8;++e){ const float p=__builtin_bit_cast(float,__builtin_amdgcn_ds_bpermute(bp,__builtin_bit_cast(int,v[0][e]))); v[0][e]=v[0][e]*cc[e]+sg*(p*sn[e]); }
;     }
;     #pragma unroll
;     for(int d0=0;d0<4;++d0){ u32x4 w; w[0]=cvtpk_s(v[d0][0]*QS,v[d0][1]*QS); w[1]=cvtpk_s(v[d0][2]*QS,v[d0][3]*QS); w[2]=cvtpk_s(v[d0][4]*QS,v[d0][5]*QS); w[3]=cvtpk_s(v[d0][6]*QS,v[d0][7]*QS);
;       qr[d0]=__builtin_bit_cast(bf16x8,w); }
;   }
;   WAIT_BAR(3);
;   qkt(pA0,pA1,Kbase+s0,qr,negm,r32,hi);asm volatile("s_nop 15\n\ts_nop 7":"+v"(pA0),"+v"(pA1));CMASK(pA0,pA1,0);
.LBB0_464:
	v_or_b32_e32 v36, s38, v244
	v_add_u32_e32 v36, s84, v36
	v_ashrrev_i32_e32 v37, 31, v36
	v_lshlrev_b64 v[36:37], 6, v[36:37]
	v_lshl_add_u64 v[36:37], s[8:9], 0, v[36:37]
	global_load_dwordx4 v[40:43], v[36:37], off
	global_load_dwordx4 v[44:47], v[36:37], off offset:16
	global_load_dwordx4 v[64:67], v[36:37], off offset:32
	global_load_dwordx4 v[68:71], v[36:37], off offset:48
	v_lshlrev_b32_e32 v74, 2, v253
	s_waitcnt vmcnt(7)
	v_and_b32_e32 v37, 0xffff0000, v32
	v_lshlrev_b32_e32 v36, 16, v32
	v_and_b32_e32 v39, 0xffff0000, v33
	v_lshlrev_b32_e32 v38, 16, v33
	v_and_b32_e32 v33, 0xffff0000, v34
	v_lshlrev_b32_e32 v32, 16, v34
	v_and_b32_e32 v81, 0xffff0000, v35
	v_lshlrev_b32_e32 v80, 16, v35
	s_waitcnt vmcnt(6)
	v_and_b32_e32 v35, 0xffff0000, v56
	v_lshlrev_b32_e32 v34, 16, v56
	v_and_b32_e32 v73, 0xffff0000, v57
	v_lshlrev_b32_e32 v72, 16, v57
	v_and_b32_e32 v57, 0xffff0000, v58
	v_lshlrev_b32_e32 v56, 16, v58
	v_xor_b32_e32 v58, 0x80, v74
	ds_bpermute_b32 v84, v58, v36
	ds_bpermute_b32 v85, v58, v37
	ds_bpermute_b32 v86, v58, v38
	ds_bpermute_b32 v87, v58, v39
	ds_bpermute_b32 v88, v58, v32
	ds_bpermute_b32 v89, v58, v33
	ds_bpermute_b32 v90, v58, v80
	ds_bpermute_b32 v91, v58, v81
	v_lshlrev_b32_e32 v92, 10, v251
	v_lshlrev_b32_e32 v93, 4, v244
	s_add_i32 s4, s15, 0
	v_pk_mul_f32 v[34:35], v[34:35], s[50:51] op_sel_hi:[1,0]
	v_pk_mul_f32 v[56:57], v[56:57], s[50:51] op_sel_hi:[1,0]
	v_pk_mul_f32 v[72:73], v[72:73], s[50:51] op_sel_hi:[1,0]
	v_add3_u32 v94, s4, v92, v93
	v_cvt_pk_bf16_f32 v162, v34, v35
	v_cvt_pk_bf16_f32 v164, v56, v57
	s_waitcnt vmcnt(3) lgkmcnt(0)
	s_barrier
	v_cvt_pk_bf16_f32 v163, v72, v73
	ds_read_b128 v[72:75], v94 offset:512
	ds_read_b128 v[76:79], v94
	v_cmp_gt_u32_e64 s[4:5], 32, v253
	v_and_b32_e32 v83, 0xffff0000, v59
	v_lshlrev_b32_e32 v82, 16, v59
	v_lshlrev_b32_e32 v63, 1, v62
	v_and_b32_e32 v223, 32, v63
	s_and_b32 s2, s2, 0x3fffffc0
	s_lshl_b32 s2, s2, 2
	s_add_i32 s65, s2, 0
	s_add_i32 s2, s47, s15
	v_add3_u32 v214, 0, v92, v93
	s_add_i32 s65, s65, 0x12000
	s_xor_b64 s[82:83], s[86:87], -1
	s_mov_b32 s13, 1
	v_lshl_add_u32 v242, v244, 2, s65
	v_lshlrev_b32_e32 v243, 4, v251
	v_lshl_add_u64 v[230:231], v[226:227], 0, s[60:61]
	v_mov_b32_e32 v215, 0
	s_mov_b32 s96, 5
	s_waitcnt vmcnt(3)
	v_mov_b32_e32 v35, v42
	v_mov_b32_e32 v42, v41
	s_waitcnt vmcnt(2)
	v_mov_b32_e32 v41, v46
	v_mov_b32_e32 v46, v45
	s_waitcnt vmcnt(1)
	v_mov_b32_e32 v45, v66
	v_mov_b32_e32 v66, v65
	s_waitcnt vmcnt(0)
	v_mov_b32_e32 v57, v70
	v_mov_b32_e32 v70, v69
	v_mov_b32_e32 v34, v40
	v_mov_b32_e32 v40, v44
	v_mov_b32_e32 v44, v64
	s_waitcnt lgkmcnt(8)
	v_pk_mul_f32 v[42:43], v[42:43], v[84:85]
	s_waitcnt lgkmcnt(6)
	v_pk_mul_f32 v[46:47], v[46:47], v[86:87]
	s_waitcnt lgkmcnt(4)
	v_pk_mul_f32 v[64:65], v[66:67], v[88:89]
	s_waitcnt lgkmcnt(2)
	v_pk_mul_f32 v[66:67], v[70:71], v[90:91]
	v_mov_b32_e32 v56, v68
	v_cndmask_b32_e64 v43, v43, -v43, s[4:5]
	v_cndmask_b32_e64 v42, v42, -v42, s[4:5]
	v_cndmask_b32_e64 v47, v47, -v47, s[4:5]
	v_cndmask_b32_e64 v46, v46, -v46, s[4:5]
	v_cndmask_b32_e64 v65, v65, -v65, s[4:5]
	v_cndmask_b32_e64 v64, v64, -v64, s[4:5]
	v_cndmask_b32_e64 v67, v67, -v67, s[4:5]
	v_cndmask_b32_e64 v66, v66, -v66, s[4:5]
	v_pk_fma_f32 v[34:35], v[34:35], v[36:37], v[42:43]
	v_pk_fma_f32 v[36:37], v[40:41], v[38:39], v[46:47]
	v_pk_fma_f32 v[32:33], v[44:45], v[32:33], v[64:65]
	v_pk_fma_f32 v[38:39], v[56:57], v[80:81], v[66:67]
	v_pk_mul_f32 v[34:35], v[34:35], s[50:51] op_sel_hi:[1,0]
	v_pk_mul_f32 v[36:37], v[36:37], s[50:51] op_sel_hi:[1,0]
	v_pk_mul_f32 v[32:33], v[32:33], s[50:51] op_sel_hi:[1,0]
	v_pk_mul_f32 v[38:39], v[38:39], s[50:51] op_sel_hi:[1,0]
	v_cvt_pk_bf16_f32 v174, v34, v35
	v_cvt_pk_bf16_f32 v175, v36, v37
	v_cvt_pk_bf16_f32 v176, v32, v33
	v_cvt_pk_bf16_f32 v177, v38, v39
	v_pk_mul_f32 v[56:57], v[82:83], s[50:51] op_sel_hi:[1,0]
	v_and_b32_e32 v69, 0xffff0000, v52
	s_waitcnt lgkmcnt(0)
	v_mfma_f32_32x32x16_bf16 v[32:47], v[76:79], v[174:177], v[16:31]
	v_cvt_pk_bf16_f32 v165, v56, v57
	ds_read_b128 v[56:59], v94 offset:2560
	ds_read_b128 v[64:67], v94 offset:2048
	v_lshlrev_b32_e32 v68, 16, v52
	v_mul_f32_e64 v68, v68, s50
	v_mul_f32_e64 v69, v69, s50
	v_cvt_pk_bf16_f32 v170, v68, v69
	v_and_b32_e32 v69, 0xffff0000, v53
	v_mfma_f32_32x32x16_bf16 v[16:31], v[72:75], v[174:177], v[16:31]
	v_lshlrev_b32_e32 v68, 16, v53
	v_mul_f32_e64 v52, v68, s50
	v_mul_f32_e64 v53, v69, s50
	v_cvt_pk_bf16_f32 v171, v52, v53
	v_and_b32_e32 v53, 0xffff0000, v54
	v_lshlrev_b32_e32 v52, 16, v54
	v_pk_mul_f32 v[52:53], v[52:53], s[50:51] op_sel_hi:[1,0]
	s_waitcnt lgkmcnt(0)
	v_mfma_f32_32x32x16_bf16 v[32:47], v[64:67], v[162:165], v[32:47]
	ds_read_b128 v[64:67], v94 offset:4608
	ds_read_b128 v[68:71], v94 offset:4096
	v_cvt_pk_bf16_f32 v172, v52, v53
	v_and_b32_e32 v53, 0xffff0000, v55
	v_lshlrev_b32_e32 v52, 16, v55
	v_pk_mul_f32 v[52:53], v[52:53], s[50:51] op_sel_hi:[1,0]
	s_nop 0
	v_cvt_pk_bf16_f32 v173, v52, v53
	v_mfma_f32_32x32x16_bf16 v[16:31], v[56:59], v[162:165], v[16:31]
	v_and_b32_e32 v53, 0xffff0000, v48
	v_lshlrev_b32_e32 v52, 16, v48
	v_mul_f32_e64 v52, v52, s50
	v_mul_f32_e64 v53, v53, s50
	v_cvt_pk_bf16_f32 v166, v52, v53
	v_and_b32_e32 v53, 0xffff0000, v49
	v_lshlrev_b32_e32 v52, 16, v49
	s_waitcnt lgkmcnt(0)
	v_mfma_f32_32x32x16_bf16 v[32:47], v[68:71], v[170:173], v[32:47]
	v_mul_f32_e64 v48, v52, s50
	v_mul_f32_e64 v49, v53, s50
	ds_read_b128 v[52:55], v94 offset:6656
	ds_read_b128 v[56:59], v94 offset:6144
	v_cvt_pk_bf16_f32 v167, v48, v49
	v_and_b32_e32 v49, 0xffff0000, v50
	v_lshlrev_b32_e32 v48, 16, v50
	v_pk_mul_f32 v[48:49], v[48:49], s[50:51] op_sel_hi:[1,0]
	v_mfma_f32_32x32x16_bf16 v[16:31], v[64:67], v[170:173], v[16:31]
	v_cvt_pk_bf16_f32 v168, v48, v49
	v_and_b32_e32 v49, 0xffff0000, v51
	v_lshlrev_b32_e32 v48, 16, v51
	v_mul_f32_e64 v48, v48, s50
	v_mul_f32_e64 v49, v49, s50
	v_cvt_pk_bf16_f32 v169, v48, v49
	v_lshlrev_b32_e32 v48, 4, v62
	v_and_b32_e32 v48, 0xc0, v48
	s_waitcnt lgkmcnt(0)
; #define WAIT_BAR(N) asm volatile("s_waitcnt vmcnt(" #N ") lgkmcnt(0)\n\ts_barrier":::"memory")
;   #define DMA_K(t,slot) glds16(ksrc+(long)(t)*KVBLK*DM,(unsigned)__builtin_amdgcn_readfirstlane(kdst+(slot)))
;   #define DMA_V(t,slot) do{ glds16(vsrc+(long)(t)*KVBLK*DM,(unsigned)__builtin_amdgcn_readfirstlane(vdst+VM*(slot))); \
;     if constexpr(DV==128){ glds16(vsrc+64+(long)(t)*KVBLK*DM,(unsigned)__builtin_amdgcn_readfirstlane(vdst+VM*(slot)+8192)); } }while(0)
;   #define WAIT_KV() do{ if constexpr(DV==128){WAIT_BAR(3);} else {WAIT_BAR(2);} }while(0)
;   #define CMASK(P0,P1,t) do{ if constexpr(WIN){ wmask(P0,P1,(t_lo+(t))*KVBLK+4*hi,qpos); } }while(0)
;   #define ROT() do{sl_prev=sl_cur;sl_cur=sl_next;sl_next=(sl_next==(NSLOT-1)*SLOTB)?0:sl_next+SLOTB;}while(0)
; template<int THRL,bool WIN,int DM,int ODM,int DV,int QMODE> __device__ __forceinline__ void attn_unit(const bf16*Qp,const bf16*__restrict__ Kp,const bf16*__restrict__ Vp,bf16*Op,const int q0,const int t_lo,const int NT,const float sink2,char*shm,const float*qgain,const float*qtab,const int b0,const ...
;     ...
;   WAIT_BAR(3);
;   qkt(pA0,pA1,Kbase+s0,qr,negm,r32,hi);asm volatile("s_nop 15\n\ts_nop 7":"+v"(pA0),"+v"(pA1));CMASK(pA0,pA1,0);
;   START(pA0,pA1);
;   _Pragma("unroll") for(int r=0;r<16;++r)pA1[r]=__builtin_amdgcn_exp2f(pA1[r]);
;   WAIT_BAR(0);
;   DMA_K(3,s0);DMA_V(1,s1);
;   ROT();
;   kload8(kf,kp0+sl_cur);
;   WAIT_KV();
;   s16x4 vlo[8],vhi[8]; u32x4 pw0,pw1,pw2,pw3;
	v_mfma_f32_32x32x16_bf16 v[32:47], v[56:59], v[166:169], v[32:47]
	v_lshl_or_b32 v221, v251, 8, v48
	v_add_u32_e32 v48, 0, v223
	v_add3_u32 v249, v48, v219, v221
	v_mfma_f32_32x32x16_bf16 v[16:31], v[52:55], v[166:169], v[16:31]
	s_nop 15
	s_nop 7
	s_nop 0
	v_max3_f32 v48, v32, v33, v16
	v_max3_f32 v49, v34, v35, v17
	s_nop 0
	v_max3_f32 v48, v48, v18, v19
	v_max3_f32 v49, v49, v38, v39
	s_nop 0
	v_max3_f32 v48, v48, v36, v37
	v_max3_f32 v49, v49, v22, v23
	s_nop 0
	v_max3_f32 v48, v48, v20, v21
	v_max3_f32 v49, v49, v42, v43
	s_nop 0
	v_max3_f32 v48, v48, v40, v41
	v_max3_f32 v49, v49, v26, v27
	s_nop 0
	v_max3_f32 v48, v48, v24, v25
	v_max3_f32 v49, v49, v46, v47
	s_nop 0
	v_max3_f32 v48, v48, v44, v45
	v_max3_f32 v49, v49, v30, v31
	s_nop 0
	v_max3_f32 v48, v48, v28, v29
	s_nop 0
	v_max_f32_e32 v48, v48, v49
	s_nop 0
	v_mov_b32_e32 v49, v48
	s_nop 1
	v_permlane32_swap_b32_e32 v48, v49
	v_max_f32_e32 v48, v48, v49
	s_nop 0
	v_add_f32_e32 v245, v0, v48
	v_sub_f32_e32 v49, v16, v48
	v_sub_f32_e32 v50, v17, v48
	v_lshl_add_u64 v[16:17], v[224:225], 0, s[56:57]
	v_xor_b32_e32 v66, 0x80000000, v245
	v_mov_b32_e32 v67, v66
	v_mov_b32_e32 v68, v66
	v_mov_b32_e32 v69, v66
	v_mov_b32_e32 v70, v66
	v_mov_b32_e32 v71, v66
	v_mov_b32_e32 v72, v66
	v_mov_b32_e32 v73, v66
	v_mov_b32_e32 v74, v66
	v_mov_b32_e32 v75, v66
	v_mov_b32_e32 v76, v66
	v_mov_b32_e32 v77, v66
	v_mov_b32_e32 v78, v66
	v_mov_b32_e32 v79, v66
	v_mov_b32_e32 v80, v66
	v_mov_b32_e32 v81, v66
	s_waitcnt vmcnt(0) lgkmcnt(0)
	s_barrier
	s_mov_b32 s6, m0
	s_mov_b32 m0, s2
	s_nop 0
	global_load_lds_dwordx4 v[16:17], off
	s_mov_b32 m0, s6
	s_lshl_b32 s2, s3, 1
	v_lshl_add_u64 v[16:17], v[226:227], 0, s[54:55]
	s_add_i32 s2, s64, s2
	s_mov_b32 s6, m0
	s_mov_b32 m0, s2
	s_nop 0
	global_load_lds_dwordx4 v[16:17], off
	s_mov_b32 m0, s6
	s_mov_b64 s[6:7], 0xe80
	v_lshl_add_u64 v[228:229], v[60:61], 0, s[6:7]
	s_mov_b64 s[6:7], 0x48080
	v_lshl_add_u64 v[16:17], v[226:227], 0, s[6:7]
	s_addk_i32 s2, 0x2000
	s_mov_b32 s6, m0
	s_mov_b32 m0, s2
	s_nop 0
	global_load_lds_dwordx4 v[16:17], off
	s_mov_b32 m0, s6
	v_add_u32_e32 v16, s3, v214
	ds_read_b128 v[206:209], v16
	ds_read_b128 v[202:205], v16 offset:512
	ds_read_b128 v[198:201], v16 offset:2048
	ds_read_b128 v[194:197], v16 offset:2560
	ds_read_b128 v[190:193], v16 offset:4096
	ds_read_b128 v[186:189], v16 offset:4608
	ds_read_b128 v[182:185], v16 offset:6144
	ds_read_b128 v[178:181], v16 offset:6656
	v_sub_f32_e32 v32, v32, v48
	v_sub_f32_e32 v33, v33, v48
	v_sub_f32_e32 v34, v34, v48
	v_sub_f32_e32 v18, v18, v48
	v_sub_f32_e32 v35, v35, v48
	v_sub_f32_e32 v19, v19, v48
	v_sub_f32_e32 v36, v36, v48
	v_sub_f32_e32 v20, v20, v48
	v_sub_f32_e32 v37, v37, v48
	v_sub_f32_e32 v21, v21, v48
	v_sub_f32_e32 v38, v38, v48
	v_sub_f32_e32 v22, v22, v48
	v_sub_f32_e32 v39, v39, v48
	v_sub_f32_e32 v23, v23, v48
	v_sub_f32_e32 v40, v40, v48
	v_sub_f32_e32 v24, v24, v48
	v_sub_f32_e32 v41, v41, v48
	v_sub_f32_e32 v25, v25, v48
	v_sub_f32_e32 v42, v42, v48
	v_sub_f32_e32 v26, v26, v48
	v_sub_f32_e32 v43, v43, v48
	v_sub_f32_e32 v27, v27, v48
	v_sub_f32_e32 v44, v44, v48
	v_sub_f32_e32 v28, v28, v48
	v_sub_f32_e32 v45, v45, v48
	v_sub_f32_e32 v29, v29, v48
	v_sub_f32_e32 v46, v46, v48
	v_sub_f32_e32 v30, v30, v48
	v_sub_f32_e32 v47, v47, v48
	v_sub_f32_e32 v31, v31, v48
	s_nop 0
	v_exp_f32_e32 v98, v32
	v_exp_f32_e32 v113, v47
	v_exp_f32_e32 v99, v33
	v_exp_f32_e32 v100, v34
	v_exp_f32_e32 v101, v35
	v_exp_f32_e32 v102, v36
	v_exp_f32_e32 v103, v37
	v_exp_f32_e32 v104, v38
	v_exp_f32_e32 v105, v39
	v_exp_f32_e32 v106, v40
	v_exp_f32_e32 v107, v41
	v_exp_f32_e32 v108, v42
	v_exp_f32_e32 v109, v43
	v_exp_f32_e32 v110, v44
	v_exp_f32_e32 v111, v45
	v_exp_f32_e32 v112, v46
	v_exp_f32_e32 v97, v31
	v_exp_f32_e32 v82, v49
	v_exp_f32_e32 v83, v50
	v_exp_f32_e32 v84, v18
	v_exp_f32_e32 v85, v19
	v_exp_f32_e32 v86, v20
	v_exp_f32_e32 v87, v21
	v_exp_f32_e32 v88, v22
	v_exp_f32_e32 v89, v23
	v_exp_f32_e32 v90, v24
	v_exp_f32_e32 v91, v25
	v_exp_f32_e32 v92, v26
	v_exp_f32_e32 v93, v27
	v_exp_f32_e32 v94, v28
	v_exp_f32_e32 v95, v29
	v_exp_f32_e32 v96, v30
	s_mov_b64 s[6:7], 0x120e80
	s_waitcnt vmcnt(3) lgkmcnt(0)
	s_barrier
	v_lshl_add_u64 v[232:233], v[60:61], 0, s[6:7]
	v_mov_b64_e32 v[64:65], v[14:15]
	v_mov_b64_e32 v[48:49], v[14:15]
	v_mov_b64_e32 v[32:33], v[14:15]
	v_mov_b64_e32 v[62:63], v[12:13]
	v_mov_b64_e32 v[60:61], v[10:11]
	v_mov_b64_e32 v[58:59], v[8:9]
	v_mov_b64_e32 v[56:57], v[6:7]
	v_mov_b64_e32 v[54:55], v[4:5]
	v_mov_b64_e32 v[52:53], v[2:3]
	v_mov_b64_e32 v[50:51], v[0:1]
	v_mov_b64_e32 v[46:47], v[12:13]
	v_mov_b64_e32 v[44:45], v[10:11]
	v_mov_b64_e32 v[42:43], v[8:9]
	v_mov_b64_e32 v[40:41], v[6:7]
	v_mov_b64_e32 v[38:39], v[4:5]
	v_mov_b64_e32 v[36:37], v[2:3]
	v_mov_b64_e32 v[34:35], v[0:1]
	v_mov_b64_e32 v[30:31], v[12:13]
	v_mov_b64_e32 v[28:29], v[10:11]
	v_mov_b64_e32 v[26:27], v[8:9]
	v_mov_b64_e32 v[24:25], v[6:7]
	v_mov_b64_e32 v[22:23], v[4:5]
	v_mov_b64_e32 v[20:21], v[2:3]
	v_mov_b64_e32 v[18:19], v[0:1]
	v_mov_b64_e32 v[16:17], v[14:15]
	s_mov_b64 s[6:7], 0
	v_mov_b64_e32 v[14:15], v[12:13]
	v_mov_b64_e32 v[12:13], v[10:11]
	v_mov_b64_e32 v[10:11], v[8:9]
	v_mov_b64_e32 v[8:9], v[6:7]
	v_mov_b64_e32 v[6:7], v[4:5]
	v_mov_b64_e32 v[4:5], v[2:3]
	v_mov_b64_e32 v[2:3], v[0:1]
	v_readfirstlane_b32 s98, v224
	v_readfirstlane_b32 s99, v225
	s_nop 1
	v_subrev_u32_e32 v234, s98, v224
	v_subrev_u32_e32 v236, s98, v226
	v_subrev_u32_e32 v238, s98, v228
	v_add_u32_e32 v235, 0x168000, v234
	v_add_u32_e32 v234, 0x120000, v234
	v_add_u32_e32 v237, 0xd8000, v236
	v_add_u32_e32 v236, 0x90000, v236
	v_add_u32_e32 v239, 0xd8000, v238
	v_add_u32_e32 v238, 0x90000, v238
.LBB0_465:
	s_lshl_b32 s2, s15, 1
	v_add_u32_e32 v216, s2, v249
	ds_read_b64_tr_b16 v[210:211], v216 offset:24576
	ds_read_b64_tr_b16 v[212:213], v216 offset:25088
	s_waitcnt lgkmcnt(9)
	v_mfma_f32_32x32x16_bf16 v[130:145], v[206:209], v[174:177], v[66:81]
	v_add_f32_e32 v1, v98, v99
	v_add_f32_e32 v1, v100, v1
	v_add_f32_e32 v1, v101, v1
	v_add_f32_e32 v1, v102, v1
	v_add_f32_e32 v1, v103, v1
	v_cvt_pk_bf16_f32 v158, v98, v99
	v_cvt_pk_bf16_f32 v159, v100, v101
	ds_read_b64_tr_b16 v[98:99], v216 offset:28672
	ds_read_b64_tr_b16 v[100:101], v216 offset:29184
	s_waitcnt lgkmcnt(10)
	v_mfma_f32_32x32x16_bf16 v[114:129], v[202:205], v[174:177], v[66:81]
	v_add_f32_e32 v1, v104, v1
	v_add_f32_e32 v1, v105, v1
	v_add_f32_e32 v1, v106, v1
	v_add_f32_e32 v1, v107, v1
	v_cvt_pk_bf16_f32 v160, v102, v103
	v_cvt_pk_bf16_f32 v161, v104, v105
	ds_read_b64_tr_b16 v[102:103], v216 offset:25600
	ds_read_b64_tr_b16 v[104:105], v216 offset:26112
	s_waitcnt lgkmcnt(11)
	v_mfma_f32_32x32x16_bf16 v[130:145], v[198:201], v[162:165], v[130:145]
	v_add_f32_e32 v1, v108, v1
	v_add_f32_e32 v1, v109, v1
	v_add_f32_e32 v1, v110, v1
	v_add_f32_e32 v1, v111, v1
	v_cvt_pk_bf16_f32 v154, v106, v107
	v_cvt_pk_bf16_f32 v155, v108, v109
	ds_read_b64_tr_b16 v[106:107], v216 offset:29696
	ds_read_b64_tr_b16 v[108:109], v216 offset:30208
	s_waitcnt lgkmcnt(12)
	v_mfma_f32_32x32x16_bf16 v[114:129], v[194:197], v[162:165], v[114:129]
	v_add_f32_e32 v1, v112, v1
	v_add_f32_e32 v1, v113, v1
	v_add_f32_e32 v1, v82, v1
	v_add_f32_e32 v1, v83, v1
	v_cvt_pk_bf16_f32 v156, v110, v111
	v_cvt_pk_bf16_f32 v157, v112, v113
	ds_read_b64_tr_b16 v[110:111], v216 offset:26624
	ds_read_b64_tr_b16 v[112:113], v216 offset:27136
	s_waitcnt lgkmcnt(13)
	v_mfma_f32_32x32x16_bf16 v[130:145], v[190:193], v[170:173], v[130:145]
	v_add_f32_e32 v1, v84, v1
	v_add_f32_e32 v1, v85, v1
	v_add_f32_e32 v1, v86, v1
	v_add_f32_e32 v1, v87, v1
	v_cvt_pk_bf16_f32 v150, v82, v83
	v_cvt_pk_bf16_f32 v151, v84, v85
	ds_read_b64_tr_b16 v[82:83], v216 offset:30720
	ds_read_b64_tr_b16 v[84:85], v216 offset:31232
	s_waitcnt lgkmcnt(14)
	v_mfma_f32_32x32x16_bf16 v[114:129], v[186:189], v[170:173], v[114:129]
	v_add_f32_e32 v1, v88, v1
	v_add_f32_e32 v1, v89, v1
	v_add_f32_e32 v1, v90, v1
	v_add_f32_e32 v1, v91, v1
	v_cvt_pk_bf16_f32 v152, v86, v87
	v_cvt_pk_bf16_f32 v153, v88, v89
	ds_read_b64_tr_b16 v[86:87], v216 offset:27648
	ds_read_b64_tr_b16 v[88:89], v216 offset:28160
	s_waitcnt lgkmcnt(14)
	v_mfma_f32_32x32x16_bf16 v[130:145], v[182:185], v[166:169], v[130:145]
	v_add_f32_e32 v1, v92, v1
	v_add_f32_e32 v1, v93, v1
	v_add_f32_e32 v1, v94, v1
	v_add_f32_e32 v1, v95, v1
	v_cvt_pk_bf16_f32 v146, v90, v91
	v_cvt_pk_bf16_f32 v147, v92, v93
	ds_read_b64_tr_b16 v[90:91], v216 offset:31744
	ds_read_b64_tr_b16 v[92:93], v216 offset:32256
	v_mfma_f32_32x32x16_bf16 v[114:129], v[178:181], v[166:169], v[114:129]
	v_add_f32_e32 v1, v96, v1
	v_add_f32_e32 v1, v97, v1
	v_cvt_pk_bf16_f32 v148, v94, v95
	v_cvt_pk_bf16_f32 v149, v96, v97
	s_add_i32 s2, s3, s47
	s_mov_b32 s14, m0
	s_mov_b32 m0, s2
	s_nop 0
	global_load_lds_dwordx4 v234, s[98:99]
	s_mov_b32 m0, s14
	s_lshl_b32 s51, s36, 1
	s_add_i32 s2, s51, s64
	s_mov_b32 s14, m0
	s_mov_b32 m0, s2
	s_nop 0
	global_load_lds_dwordx4 v236, s[98:99]
	s_mov_b32 m0, s14
	s_addk_i32 s2, 0x2000
	s_mov_b32 s14, m0
	s_mov_b32 m0, s2
	s_nop 0
	global_load_lds_dwordx4 v238, s[98:99]
	s_mov_b32 m0, s14
	v_max_f32_e32 v94, v130, v131
	v_max3_f32 v95, v132, v133, v115
	v_max3_f32 v94, v94, v114, v116
	v_max3_f32 v94, v94, v117, v134
	v_max3_f32 v95, v95, v136, v137
	v_max3_f32 v94, v94, v135, v118
	v_max3_f32 v95, v95, v120, v121
	v_max3_f32 v94, v94, v119, v138
	v_max3_f32 v95, v95, v140, v141
	v_max3_f32 v94, v94, v139, v122
	v_max3_f32 v95, v95, v124, v125
	v_max3_f32 v94, v94, v123, v142
	v_max3_f32 v95, v95, v144, v145
	v_max3_f32 v94, v94, v143, v126
	v_max3_f32 v95, v95, v128, v129
	v_max3_f32 v94, v94, v127, v95
	v_cmp_lt_f32_e32 vcc, s19, v94
	s_cmp_lg_u64 vcc, 0
	v_add_f32_e32 v1, v215, v1
	s_cselect_b64 s[92:93], -1, 0
	s_cbranch_vccnz .LBB0_473

.LBB0_468:
	s_add_i32 s2, s36, 0x2000
	s_cmpk_lg_i32 s36, 0x4000
	s_cselect_b32 s14, s2, 0
	s_lshl_b32 s2, s3, 1
	v_add_u32_e32 v210, s2, v249
	ds_read_b64_tr_b16 v[190:191], v210 offset:24576
	ds_read_b64_tr_b16 v[192:193], v210 offset:25088
	s_waitcnt lgkmcnt(9)
	v_mfma_f32_32x32x16_bf16 v[98:113], v[82:85], v[174:177], v[66:81]
	v_add_f32_e32 v86, v130, v131
	v_add_f32_e32 v86, v132, v86
	v_add_f32_e32 v86, v133, v86
	v_add_f32_e32 v86, v134, v86
	v_add_f32_e32 v86, v135, v86
	v_cvt_pk_bf16_f32 v158, v130, v131
	v_cvt_pk_bf16_f32 v159, v132, v133
	ds_read_b64_tr_b16 v[130:131], v210 offset:28672
	ds_read_b64_tr_b16 v[132:133], v210 offset:29184
	v_add_f32_e32 v82, v136, v86
	v_add_f32_e32 v82, v137, v82
	v_add_f32_e32 v82, v138, v82
	v_add_f32_e32 v146, v139, v82
	s_waitcnt lgkmcnt(10)
	v_mfma_f32_32x32x16_bf16 v[82:97], v[202:205], v[174:177], v[66:81]
	v_cvt_pk_bf16_f32 v160, v134, v135
	v_cvt_pk_bf16_f32 v161, v136, v137
	ds_read_b64_tr_b16 v[134:135], v210 offset:25600
	ds_read_b64_tr_b16 v[136:137], v210 offset:26112
	s_waitcnt lgkmcnt(11)
	v_mfma_f32_32x32x16_bf16 v[98:113], v[206:209], v[162:165], v[98:113]
	v_add_f32_e32 v146, v140, v146
	v_add_f32_e32 v146, v141, v146
	v_add_f32_e32 v146, v142, v146
	v_add_f32_e32 v146, v143, v146
	v_cvt_pk_bf16_f32 v154, v138, v139
	v_cvt_pk_bf16_f32 v155, v140, v141
	ds_read_b64_tr_b16 v[138:139], v210 offset:29696
	ds_read_b64_tr_b16 v[140:141], v210 offset:30208
	s_waitcnt lgkmcnt(12)
	v_mfma_f32_32x32x16_bf16 v[82:97], v[198:201], v[162:165], v[82:97]
	v_add_f32_e32 v146, v144, v146
	v_add_f32_e32 v146, v145, v146
	v_add_f32_e32 v146, v114, v146
	v_add_f32_e32 v146, v115, v146
	v_cvt_pk_bf16_f32 v156, v142, v143
	v_cvt_pk_bf16_f32 v157, v144, v145
	ds_read_b64_tr_b16 v[142:143], v210 offset:26624
	ds_read_b64_tr_b16 v[144:145], v210 offset:27136
	s_waitcnt lgkmcnt(13)
	v_mfma_f32_32x32x16_bf16 v[98:113], v[194:197], v[170:173], v[98:113]
	v_add_f32_e32 v146, v116, v146
	v_add_f32_e32 v146, v117, v146
	v_add_f32_e32 v146, v118, v146
	v_add_f32_e32 v146, v119, v146
	v_cvt_pk_bf16_f32 v150, v114, v115
	v_cvt_pk_bf16_f32 v151, v116, v117
	ds_read_b64_tr_b16 v[114:115], v210 offset:30720
	ds_read_b64_tr_b16 v[116:117], v210 offset:31232
	s_waitcnt lgkmcnt(14)
	v_mfma_f32_32x32x16_bf16 v[82:97], v[186:189], v[170:173], v[82:97]
	v_add_f32_e32 v146, v120, v146
	v_add_f32_e32 v146, v121, v146
	v_add_f32_e32 v146, v122, v146
	v_add_f32_e32 v146, v123, v146
	v_cvt_pk_bf16_f32 v152, v118, v119
	v_cvt_pk_bf16_f32 v153, v120, v121
	ds_read_b64_tr_b16 v[118:119], v210 offset:27648
	ds_read_b64_tr_b16 v[120:121], v210 offset:28160
	s_waitcnt lgkmcnt(14)
	v_mfma_f32_32x32x16_bf16 v[98:113], v[182:185], v[166:169], v[98:113]
	v_add_f32_e32 v146, v124, v146
	v_add_f32_e32 v146, v125, v146
	v_add_f32_e32 v146, v126, v146
	v_add_f32_e32 v182, v127, v146
	v_cvt_pk_bf16_f32 v146, v122, v123
	v_cvt_pk_bf16_f32 v147, v124, v125
	ds_read_b64_tr_b16 v[122:123], v210 offset:31744
	ds_read_b64_tr_b16 v[124:125], v210 offset:32256
	v_mfma_f32_32x32x16_bf16 v[82:97], v[178:181], v[166:169], v[82:97]
	v_add_f32_e32 v148, v128, v182
	v_add_f32_e32 v178, v129, v148
	v_cvt_pk_bf16_f32 v148, v126, v127
	v_cvt_pk_bf16_f32 v149, v128, v129
	s_add_i32 s2, s36, s47
	s_mov_b32 s3, m0
	s_mov_b32 m0, s2
	s_nop 0
	global_load_lds_dwordx4 v235, s[98:99]
	s_mov_b32 m0, s3
	s_lshl_b32 s2, s14, 1
	s_add_i32 s2, s2, s64
	s_mov_b32 s3, m0
	s_mov_b32 m0, s2
	s_nop 0
	global_load_lds_dwordx4 v237, s[98:99]
	s_mov_b32 m0, s3
	s_addk_i32 s2, 0x2000
	s_mov_b32 s3, m0
	s_mov_b32 m0, s2
	s_nop 0
	global_load_lds_dwordx4 v239, s[98:99]
	s_mov_b32 m0, s3
	v_max_f32_e32 v126, v98, v99
	v_max3_f32 v127, v100, v101, v83
	v_max3_f32 v126, v126, v82, v84
	v_max3_f32 v126, v126, v85, v102
	v_max3_f32 v127, v127, v104, v105
	v_max3_f32 v126, v126, v103, v86
	v_max3_f32 v127, v127, v88, v89
	v_max3_f32 v126, v126, v87, v106
	v_max3_f32 v127, v127, v108, v109
	v_max3_f32 v126, v126, v107, v90
	v_max3_f32 v127, v127, v92, v93
	v_max3_f32 v126, v126, v91, v110
	v_max3_f32 v127, v127, v112, v113
	v_max3_f32 v126, v126, v111, v94
	v_max3_f32 v127, v127, v96, v97
	v_add_f32_e32 v215, v1, v178
	v_max3_f32 v1, v126, v95, v127
	v_cmp_lt_f32_e32 vcc, s19, v1
	s_cmp_lg_u64 vcc, 0
	s_cselect_b64 s[92:93], -1, 0
	s_cbranch_vccnz .LBB0_476

;   #define WAIT_KV() do{ if constexpr(DV==128){WAIT_BAR(3);} else {WAIT_BAR(2);} }while(0)
;   #define RESC() do{ if(resc){ asm volatile("s_waitcnt lgkmcnt(0)":::"memory"); \
;       _Pragma("unroll") for(int d_=0;d_<DV/32;++d_) _Pragma("unroll") for(int r=0;r<16;++r)o[d_][r]*=wsf[crow(r,hi)]; } }while(0)
;   #define ROT() do{sl_prev=sl_cur;sl_cur=sl_next;sl_next=(sl_next==(NSLOT-1)*SLOTB)?0:sl_next+SLOTB;}while(0)
; template<int THRL,bool WIN,int DM,int ODM,int DV,int QMODE> __device__ __forceinline__ void attn_unit(const bf16*Qp,const bf16*__restrict__ Kp,const bf16*__restrict__ Vp,bf16*Op,const int q0,const int t_lo,const int NT,const float sink2,char*shm,const float*qgain,const float*qtab,const int b0,const ...
;     ...
;   int t=1;
;   for(;t+5<NT;t+=2){
;     STEP(pB0,pB1,pA0,pA1,t,true,true,true);     WAIT_KV(); RESC(); ROT();
;     STEP(pA0,pA1,pB0,pB1,t+1,true,true,true);   WAIT_KV(); RESC(); ROT();
;   }
.LBB0_471:
	s_add_i32 s13, s13, 2
	s_add_i32 s2, s14, 0x2000
	s_cmpk_lg_i32 s14, 0x4000
	s_cselect_b32 s2, s2, 0
	s_add_u32 s6, s6, 0x90000
	s_addc_u32 s7, s7, 0
	s_add_u32 s98, s98, 0x90000
	s_addc_u32 s99, s99, 0
	s_add_i32 s3, s96, 2
	s_cmp_ge_u32 s13, s24
	s_cbranch_scc1 .Lmy_b_exit
	s_mov_b32 s96, s3
	s_mov_b32 s15, s36
	s_mov_b32 s3, s14
	s_mov_b32 s36, s2
	s_branch .LBB0_465
.Lmy_b_exit:
	s_sub_u32 s100, s6, 0x90000
	s_subb_u32 s101, s7, 0
	v_lshl_add_u64 v[230:231], v[230:231], 0, s[100:101]
	v_lshl_add_u64 v[232:233], v[232:233], 0, s[100:101]
	s_branch .LBB0_479

; __global__ void __launch_bounds__(NWAVES * 64, 2) encoder_fwd(Args args) {
	.amdhsa_kernel _Z11encoder_fwd4Args
		.amdhsa_group_segment_fixed_size 0
		.amdhsa_private_segment_fixed_size 0
		.amdhsa_kernarg_size 392
		.amdhsa_user_sgpr_count 2
		.amdhsa_user_sgpr_dispatch_ptr 0
		.amdhsa_user_sgpr_queue_ptr 0
		.amdhsa_user_sgpr_kernarg_segment_ptr 1
		.amdhsa_user_sgpr_dispatch_id 0
		.amdhsa_user_sgpr_kernarg_preload_length 0
		.amdhsa_user_sgpr_kernarg_preload_offset 0
		.amdhsa_user_sgpr_private_segment_size 0
		.amdhsa_uses_dynamic_stack 0
		.amdhsa_enable_private_segment 0
		.amdhsa_system_sgpr_workgroup_id_x 1
		.amdhsa_system_sgpr_workgroup_id_y 0
		.amdhsa_system_sgpr_workgroup_id_z 0
		.amdhsa_system_sgpr_workgroup_info 0
		.amdhsa_system_vgpr_workitem_id 2
		.amdhsa_next_free_vgpr 256
		.amdhsa_next_free_sgpr 102
		.amdhsa_accum_offset 256
		.amdhsa_reserve_vcc 1
		.amdhsa_float_round_mode_32 0
		.amdhsa_float_round_mode_16_64 0
		.amdhsa_float_denorm_mode_32 3
		.amdhsa_float_denorm_mode_16_64 3
		.amdhsa_dx10_clamp 1
		.amdhsa_ieee_mode 1
		.amdhsa_fp16_overflow 0
		.amdhsa_tg_split 0
		.amdhsa_exception_fp_ieee_invalid_op 0
		.amdhsa_exception_fp_denorm_src 0
		.amdhsa_exception_fp_ieee_div_zero 0
		.amdhsa_exception_fp_ieee_overflow 0
		.amdhsa_exception_fp_ieee_underflow 0
		.amdhsa_exception_fp_ieee_inexact 0
		.amdhsa_exception_int_div_zero 0
	.end_amdhsa_kernel

; __global__ void __launch_bounds__(NWAVES * 64, 2) encoder_fwd(Args args) {
amdhsa.kernels:
  - .agpr_count:     0
    .args:
      - .offset:         0
        .size:           136
        .value_kind:     by_value
      - .offset:         136
        .size:           4
        .value_kind:     hidden_block_count_x
      - .offset:         140
        .size:           4
        .value_kind:     hidden_block_count_y
      - .offset:         144
        .size:           4
        .value_kind:     hidden_block_count_z
      - .offset:         148
        .size:           2
        .value_kind:     hidden_group_size_x
      - .offset:         150
        .size:           2
        .value_kind:     hidden_group_size_y
      - .offset:         152
        .size:           2
        .value_kind:     hidden_group_size_z
      - .offset:         154
        .size:           2
        .value_kind:     hidden_remainder_x
      - .offset:         156
        .size:           2
        .value_kind:     hidden_remainder_y
      - .offset:         158
        .size:           2
        .value_kind:     hidden_remainder_z
      - .offset:         176
        .size:           8
        .value_kind:     hidden_global_offset_x
      - .offset:         184
        .size:           8
        .value_kind:     hidden_global_offset_y
      - .offset:         192
        .size:           8
        .value_kind:     hidden_global_offset_z
      - .offset:         200
        .size:           2
        .value_kind:     hidden_grid_dims
      - .offset:         224
        .size:           8
        .value_kind:     hidden_multigrid_sync_arg
      - .offset:         256
        .size:           4
        .value_kind:     hidden_dynamic_lds_size
    .group_segment_fixed_size: 0
    .kernarg_segment_align: 8
    .kernarg_segment_size: 392
    .language:       OpenCL C
    .language_version:
      - 2
      - 0
    .max_flat_workgroup_size: 512
    .name:           _Z11encoder_fwd4Args
    .private_segment_fixed_size: 0
    .sgpr_count:     108
    .sgpr_spill_count: 49
    .symbol:         _Z11encoder_fwd4Args.kd
    .uniform_work_group_size: 1
    .uses_dynamic_stack: false
    .vgpr_count:     256
    .vgpr_spill_count: 0
    .wavefront_size: 64
